# GEMM K-loops: removed per-segment s_setprio toggling (64 instructions)
# baseline (speedup 1.0000x reference)
; #define PG8_STAGE(bufoff, gbase, voff) do { _Pragma("unroll") for (int _i = 0; _i < 2; ++_i) \
;         __builtin_amdgcn_global_load_lds((const unsigned*)((const char*)(gbase) + (voff)[_i]), (PG8_LAS unsigned*)(lds + (bufoff) + ldsw + _i * 8192), 16, 0, 0); } while (0)
; #define PG8_LDA(dst, b, h) do { _Pragma("unroll") for (int m = 0; m < 4; ++m) _Pragma("unroll") for (int k = 0; k < 2; ++k) dst[m][k] = *(const PG8_LAS bf16x8*)(lds + PG8_SA(b, h) + aoff + m * 2048 + k * 1024); } while (0)
; #define PG8_LDB(dst, b, h) do { _Pragma("unroll") for (int n = 0; n < 2; ++n) _Pragma("unroll") for (int k = 0; k < 2; ++k) dst[n][k] = *(const PG8_LAS bf16x8*)(lds + PG8_SB(b, h) + boff + n * 2048 + k * 1024); } while (0)
; #define PG8_MMA(ai, bj, At, Bt) do { __builtin_amdgcn_s_setprio(1); _Pragma("unroll") for (int m = 0; m < 4; ++m) _Pragma("unroll") for (int n = 0; n < 2; ++n) _Pragma("unroll") for (int k = 0; k < 2; ++k) \
;         acc[ai][bj][m][n] = __builtin_amdgcn_mfma_f32_16x16x32_bf16(Bt[n][k], At[m][k], acc[ai][bj][m][n], 0, 0, 0); __builtin_amdgcn_s_setprio(0); } while (0)
; #define PG8_WAIT_V(n) asm volatile("s_waitcnt vmcnt(" #n ")" ::: "memory")
; #define PG8_WAIT_L(n) asm volatile("s_waitcnt lgkmcnt(" #n ")" ::: "memory")
; #define PG8_BAR __builtin_amdgcn_s_barrier()
; template <class Epi, class Sched, bool ALIGN_EPI = false, bool SP2 = false>
; __device__ __forceinline__ void gemm_phase(PG8_LAS unsigned char* lds, const Gemm g, const Sched& S, const Epi& E) {
;     ...
;             const char* a1 = cA + (size_t)(t + 1) * kstep;
;             const char* a2 = last ? nA : cA + (size_t)(t + 2) * kstep; const char* b2 = last ? nB : cB + (size_t)(t + 2) * kstep;
;             const char* a3 = a2 + kstep; const char* b3 = b2 + kstep;
;             if (last && has_next) S.a_ready(nxt);
;             if constexpr (SP2) {
;             PG8_LDB(B0, 0, 0); PG8_LDB(B1, 0, 1); PG8_SCHED; PG8_LDA(At, 0, 0); PG8_STAGE(PG8_SA(1, 1), a1 + hstep, voffA);
;             PG8_WAIT_V(8); PG8_WAIT_L(0); PG8_BAR; PG8_MMA(0, 0, At, B0); PG8_MMA(0, 1, At, B1); PG8_BAR; PG8_SCHED;
;             PG8_LDA(At, 0, 1); PG8_STAGE(PG8_SB(0, 0), b2, voffB); PG8_STAGE(PG8_SB(0, 1), b2 + hstep, voffB); PG8_STAGE(PG8_SA(0, 0), a2, voffA);
;             PG8_WAIT_V(8); PG8_WAIT_L(0); PG8_BAR; PG8_MMA(1, 0, At, B0); PG8_MMA(1, 1, At, B1); PG8_BAR; PG8_SCHED;
.LBB0_90:
	s_add_u32 s2, s20, 0xfffc0080
	s_addc_u32 s3, s21, -1
	s_add_i32 s43, 0, 0x10000
	s_cmp_eq_u32 s42, 12
	s_cselect_b32 s25, s15, s3
	s_cselect_b32 s24, s38, s2
	v_add_u32_e32 v152, s43, v155
	s_cselect_b32 s23, s13, s41
	s_cselect_b32 s22, s39, s40
	s_add_i32 s44, 0, 0x14000
	ds_read_b128 v[148:151], v152
	ds_read_b128 v[158:161], v152 offset:1024
	ds_read_b128 v[162:165], v152 offset:2048
	ds_read_b128 v[188:191], v152 offset:3072
	v_add_u32_e32 v152, s44, v155
	ds_read_b128 v[192:195], v152
	ds_read_b128 v[202:205], v152 offset:1024
	ds_read_b128 v[206:209], v152 offset:2048
	ds_read_b128 v[210:213], v152 offset:3072
	v_lshl_add_u64 v[152:153], s[20:21], 0, v[144:145]
	s_add_i32 m0, s27, 0xc000
	ds_read_b128 v[214:217], v157
	ds_read_b128 v[218:221], v157 offset:1024
	ds_read_b128 v[222:225], v157 offset:2048
	ds_read_b128 v[226:229], v157 offset:3072
	ds_read_b128 v[230:233], v157 offset:4096
	ds_read_b128 v[234:237], v157 offset:5120
	ds_read_b128 v[238:241], v157 offset:6144
	ds_read_b128 v[242:245], v157 offset:7168
	global_load_lds_dwordx4 v[152:153], off
	v_lshl_add_u64 v[152:153], s[20:21], 0, v[146:147]
	s_add_i32 m0, s27, 0xe000
	s_nop 0
	global_load_lds_dwordx4 v[152:153], off
	s_waitcnt vmcnt(8)
	s_waitcnt lgkmcnt(0)
	s_barrier
	s_waitcnt lgkmcnt(0)
	v_mfma_f32_16x16x32_bf16 v[126:129], v[148:151], v[214:217], v[126:129]
	v_mfma_f32_16x16x32_bf16 v[122:125], v[162:165], v[214:217], v[122:125]
	v_mfma_f32_16x16x32_bf16 v[110:113], v[148:151], v[222:225], v[110:113]
	v_mfma_f32_16x16x32_bf16 v[106:109], v[162:165], v[222:225], v[106:109]
	v_mfma_f32_16x16x32_bf16 v[94:97], v[148:151], v[230:233], v[94:97]
	v_mfma_f32_16x16x32_bf16 v[90:93], v[162:165], v[230:233], v[90:93]
	v_mfma_f32_16x16x32_bf16 v[78:81], v[148:151], v[238:241], v[78:81]
	v_mfma_f32_16x16x32_bf16 v[74:77], v[162:165], v[238:241], v[74:77]
	v_mfma_f32_16x16x32_bf16 v[126:129], v[158:161], v[218:221], v[126:129]
	v_mfma_f32_16x16x32_bf16 v[122:125], v[188:191], v[218:221], v[122:125]
	v_mfma_f32_16x16x32_bf16 v[110:113], v[158:161], v[226:229], v[110:113]
	v_mfma_f32_16x16x32_bf16 v[106:109], v[188:191], v[226:229], v[106:109]
	v_mfma_f32_16x16x32_bf16 v[94:97], v[158:161], v[234:237], v[94:97]
	v_mfma_f32_16x16x32_bf16 v[90:93], v[188:191], v[234:237], v[90:93]
	v_mfma_f32_16x16x32_bf16 v[78:81], v[158:161], v[242:245], v[78:81]
	v_mfma_f32_16x16x32_bf16 v[74:77], v[188:191], v[242:245], v[74:77]
	v_mfma_f32_16x16x32_bf16 v[118:121], v[192:195], v[214:217], v[118:121]
	v_mfma_f32_16x16x32_bf16 v[114:117], v[206:209], v[214:217], v[114:117]
	v_mfma_f32_16x16x32_bf16 v[102:105], v[192:195], v[222:225], v[102:105]
	v_mfma_f32_16x16x32_bf16 v[98:101], v[206:209], v[222:225], v[98:101]
	v_mfma_f32_16x16x32_bf16 v[86:89], v[192:195], v[230:233], v[86:89]
	v_mfma_f32_16x16x32_bf16 v[82:85], v[206:209], v[230:233], v[82:85]
	v_mfma_f32_16x16x32_bf16 v[70:73], v[192:195], v[238:241], v[70:73]
	v_mfma_f32_16x16x32_bf16 v[66:69], v[206:209], v[238:241], v[66:69]
	v_mfma_f32_16x16x32_bf16 v[118:121], v[202:205], v[218:221], v[118:121]
	v_mfma_f32_16x16x32_bf16 v[114:117], v[210:213], v[218:221], v[114:117]
	v_mfma_f32_16x16x32_bf16 v[102:105], v[202:205], v[226:229], v[102:105]
	v_mfma_f32_16x16x32_bf16 v[98:101], v[210:213], v[226:229], v[98:101]
	v_mfma_f32_16x16x32_bf16 v[86:89], v[202:205], v[234:237], v[86:89]
	v_mfma_f32_16x16x32_bf16 v[82:85], v[210:213], v[234:237], v[82:85]
	v_mfma_f32_16x16x32_bf16 v[70:73], v[202:205], v[242:245], v[70:73]
	v_mfma_f32_16x16x32_bf16 v[66:69], v[210:213], v[242:245], v[66:69]
	s_barrier
	s_add_i32 s2, s43, s26
	v_lshl_add_u64 v[152:153], s[22:23], 0, v[0:1]
	s_mov_b32 m0, s2
	ds_read_b128 v[214:217], v157 offset:16384
	ds_read_b128 v[218:221], v157 offset:17408
	ds_read_b128 v[222:225], v157 offset:18432
	ds_read_b128 v[226:229], v157 offset:19456
	ds_read_b128 v[230:233], v157 offset:20480
	ds_read_b128 v[234:237], v157 offset:21504
	ds_read_b128 v[238:241], v157 offset:22528
	ds_read_b128 v[242:245], v157 offset:23552
	global_load_lds_dwordx4 v[152:153], off
	s_add_i32 m0, s2, 0x2000
	s_add_u32 s2, s22, 0x40000
	v_lshl_add_u64 v[166:167], s[22:23], 0, v[138:139]
	s_addc_u32 s3, s23, 0
	s_add_i32 s43, s44, s26
	global_load_lds_dwordx4 v[166:167], off
	v_lshl_add_u64 v[196:197], s[2:3], 0, v[0:1]
	s_mov_b32 m0, s43
	v_lshl_add_u64 v[246:247], s[24:25], 0, v[140:141]
	global_load_lds_dwordx4 v[196:197], off
	v_lshl_add_u64 v[196:197], s[2:3], 0, v[138:139]
	s_add_i32 m0, s43, 0x2000
	s_nop 0
	global_load_lds_dwordx4 v[196:197], off
	v_lshl_add_u64 v[196:197], s[24:25], 0, v[142:143]
	s_mov_b32 m0, s27
	s_nop 0
	global_load_lds_dwordx4 v[196:197], off
	s_mov_b32 m0, s28
	s_nop 0
	global_load_lds_dwordx4 v[246:247], off
	s_waitcnt vmcnt(8)
	s_waitcnt lgkmcnt(0)
	s_barrier
; #define PG8_STAGE(bufoff, gbase, voff) do { _Pragma("unroll") for (int _i = 0; _i < 2; ++_i) \
;         __builtin_amdgcn_global_load_lds((const unsigned*)((const char*)(gbase) + (voff)[_i]), (PG8_LAS unsigned*)(lds + (bufoff) + ldsw + _i * 8192), 16, 0, 0); } while (0)
; #define PG8_LDA(dst, b, h) do { _Pragma("unroll") for (int m = 0; m < 4; ++m) _Pragma("unroll") for (int k = 0; k < 2; ++k) dst[m][k] = *(const PG8_LAS bf16x8*)(lds + PG8_SA(b, h) + aoff + m * 2048 + k * 1024); } while (0)
; #define PG8_LDB(dst, b, h) do { _Pragma("unroll") for (int n = 0; n < 2; ++n) _Pragma("unroll") for (int k = 0; k < 2; ++k) dst[n][k] = *(const PG8_LAS bf16x8*)(lds + PG8_SB(b, h) + boff + n * 2048 + k * 1024); } while (0)
; #define PG8_MMA(ai, bj, At, Bt) do { __builtin_amdgcn_s_setprio(1); _Pragma("unroll") for (int m = 0; m < 4; ++m) _Pragma("unroll") for (int n = 0; n < 2; ++n) _Pragma("unroll") for (int k = 0; k < 2; ++k) \
;         acc[ai][bj][m][n] = __builtin_amdgcn_mfma_f32_16x16x32_bf16(Bt[n][k], At[m][k], acc[ai][bj][m][n], 0, 0, 0); __builtin_amdgcn_s_setprio(0); } while (0)
; #define PG8_WAIT_V(n) asm volatile("s_waitcnt vmcnt(" #n ")" ::: "memory")
; #define PG8_WAIT_L(n) asm volatile("s_waitcnt lgkmcnt(" #n ")" ::: "memory")
; #define PG8_BAR __builtin_amdgcn_s_barrier()
; #define PG8_SCHED __builtin_amdgcn_sched_barrier(0)
; template <class Epi, class Sched, bool ALIGN_EPI = false, bool SP2 = false>
; __device__ __forceinline__ void gemm_phase(PG8_LAS unsigned char* lds, const Gemm g, const Sched& S, const Epi& E) {
;     ...
;             PG8_WAIT_V(8); PG8_WAIT_L(0); PG8_BAR; PG8_MMA(1, 0, At, B0); PG8_MMA(1, 1, At, B1); PG8_BAR; PG8_SCHED;
;             PG8_LDB(B0, 1, 0); PG8_LDB(B1, 1, 1); PG8_SCHED; PG8_LDA(At, 1, 0); PG8_STAGE(PG8_SA(0, 1), a2 + hstep, voffA);
;             PG8_WAIT_V(8); PG8_WAIT_L(0); PG8_BAR; PG8_MMA(0, 0, At, B0); PG8_MMA(0, 1, At, B1); PG8_BAR; PG8_SCHED;
	s_waitcnt lgkmcnt(0)
	v_mfma_f32_16x16x32_bf16 v[62:65], v[148:151], v[214:217], v[62:65]
	v_mfma_f32_16x16x32_bf16 v[58:61], v[162:165], v[214:217], v[58:61]
	v_mfma_f32_16x16x32_bf16 v[46:49], v[148:151], v[222:225], v[46:49]
	v_mfma_f32_16x16x32_bf16 v[42:45], v[162:165], v[222:225], v[42:45]
	v_mfma_f32_16x16x32_bf16 v[30:33], v[148:151], v[230:233], v[30:33]
	v_mfma_f32_16x16x32_bf16 v[26:29], v[162:165], v[230:233], v[26:29]
	v_mfma_f32_16x16x32_bf16 v[14:17], v[148:151], v[238:241], v[14:17]
	v_mfma_f32_16x16x32_bf16 v[10:13], v[162:165], v[238:241], v[10:13]
	v_mfma_f32_16x16x32_bf16 v[62:65], v[158:161], v[218:221], v[62:65]
	v_mfma_f32_16x16x32_bf16 v[58:61], v[188:191], v[218:221], v[58:61]
	v_mfma_f32_16x16x32_bf16 v[46:49], v[158:161], v[226:229], v[46:49]
	v_mfma_f32_16x16x32_bf16 v[42:45], v[188:191], v[226:229], v[42:45]
	v_mfma_f32_16x16x32_bf16 v[30:33], v[158:161], v[234:237], v[30:33]
	v_mfma_f32_16x16x32_bf16 v[26:29], v[188:191], v[234:237], v[26:29]
	v_mfma_f32_16x16x32_bf16 v[14:17], v[158:161], v[242:245], v[14:17]
	v_mfma_f32_16x16x32_bf16 v[10:13], v[188:191], v[242:245], v[10:13]
	v_mfma_f32_16x16x32_bf16 v[54:57], v[192:195], v[214:217], v[54:57]
	v_mfma_f32_16x16x32_bf16 v[50:53], v[206:209], v[214:217], v[50:53]
	v_mfma_f32_16x16x32_bf16 v[38:41], v[192:195], v[222:225], v[38:41]
	v_mfma_f32_16x16x32_bf16 v[34:37], v[206:209], v[222:225], v[34:37]
	v_mfma_f32_16x16x32_bf16 v[22:25], v[192:195], v[230:233], v[22:25]
	v_mfma_f32_16x16x32_bf16 v[18:21], v[206:209], v[230:233], v[18:21]
	v_mfma_f32_16x16x32_bf16 v[6:9], v[192:195], v[238:241], v[6:9]
	v_mfma_f32_16x16x32_bf16 v[2:5], v[206:209], v[238:241], v[2:5]
	v_mfma_f32_16x16x32_bf16 v[54:57], v[202:205], v[218:221], v[54:57]
	v_mfma_f32_16x16x32_bf16 v[50:53], v[210:213], v[218:221], v[50:53]
	v_mfma_f32_16x16x32_bf16 v[38:41], v[202:205], v[226:229], v[38:41]
	v_mfma_f32_16x16x32_bf16 v[34:37], v[210:213], v[226:229], v[34:37]
	v_mfma_f32_16x16x32_bf16 v[22:25], v[202:205], v[234:237], v[22:25]
	v_mfma_f32_16x16x32_bf16 v[18:21], v[210:213], v[234:237], v[18:21]
	v_mfma_f32_16x16x32_bf16 v[6:9], v[202:205], v[242:245], v[6:9]
	v_mfma_f32_16x16x32_bf16 v[2:5], v[210:213], v[242:245], v[2:5]
	s_barrier
	s_add_i32 s43, 0, 0x18000
	s_add_i32 s44, 0, 0x1c000
	v_add_u32_e32 v188, s43, v155
	v_add_u32_e32 v210, s44, v155
	ds_read_b128 v[148:151], v188
	ds_read_b128 v[158:161], v188 offset:1024
	ds_read_b128 v[162:165], v188 offset:2048
	ds_read_b128 v[188:191], v188 offset:3072
	ds_read_b128 v[192:195], v210
	ds_read_b128 v[202:205], v210 offset:1024
	ds_read_b128 v[206:209], v210 offset:2048
	ds_read_b128 v[210:213], v210 offset:3072
	s_add_u32 s2, s24, 0x40000
	s_addc_u32 s3, s25, 0
	s_mov_b32 m0, s29
	v_lshl_add_u64 v[248:249], s[2:3], 0, v[142:143]
	ds_read_b128 v[214:217], v157 offset:32768
	ds_read_b128 v[218:221], v157 offset:33792
	ds_read_b128 v[222:225], v157 offset:34816
	ds_read_b128 v[226:229], v157 offset:35840
	ds_read_b128 v[230:233], v157 offset:36864
	ds_read_b128 v[234:237], v157 offset:37888
	ds_read_b128 v[238:241], v157 offset:38912
	ds_read_b128 v[242:245], v157 offset:39936
	global_load_lds_dwordx4 v[248:249], off
	v_lshl_add_u64 v[248:249], s[2:3], 0, v[140:141]
	s_mov_b32 m0, s30
	s_nop 0
	global_load_lds_dwordx4 v[248:249], off
	s_waitcnt vmcnt(8)
	s_waitcnt lgkmcnt(0)
	s_barrier
	s_waitcnt lgkmcnt(0)
	v_mfma_f32_16x16x32_bf16 v[126:129], v[148:151], v[214:217], v[126:129]
	v_mfma_f32_16x16x32_bf16 v[122:125], v[162:165], v[214:217], v[122:125]
	v_mfma_f32_16x16x32_bf16 v[110:113], v[148:151], v[222:225], v[110:113]
	v_mfma_f32_16x16x32_bf16 v[106:109], v[162:165], v[222:225], v[106:109]
	v_mfma_f32_16x16x32_bf16 v[94:97], v[148:151], v[230:233], v[94:97]
	v_mfma_f32_16x16x32_bf16 v[90:93], v[162:165], v[230:233], v[90:93]
	v_mfma_f32_16x16x32_bf16 v[78:81], v[148:151], v[238:241], v[78:81]
	v_mfma_f32_16x16x32_bf16 v[74:77], v[162:165], v[238:241], v[74:77]
	v_mfma_f32_16x16x32_bf16 v[126:129], v[158:161], v[218:221], v[126:129]
	v_mfma_f32_16x16x32_bf16 v[122:125], v[188:191], v[218:221], v[122:125]
	v_mfma_f32_16x16x32_bf16 v[110:113], v[158:161], v[226:229], v[110:113]
	v_mfma_f32_16x16x32_bf16 v[106:109], v[188:191], v[226:229], v[106:109]
	v_mfma_f32_16x16x32_bf16 v[94:97], v[158:161], v[234:237], v[94:97]
	v_mfma_f32_16x16x32_bf16 v[90:93], v[188:191], v[234:237], v[90:93]
	v_mfma_f32_16x16x32_bf16 v[78:81], v[158:161], v[242:245], v[78:81]
	v_mfma_f32_16x16x32_bf16 v[74:77], v[188:191], v[242:245], v[74:77]
	v_mfma_f32_16x16x32_bf16 v[118:121], v[192:195], v[214:217], v[118:121]
	v_mfma_f32_16x16x32_bf16 v[114:117], v[206:209], v[214:217], v[114:117]
	v_mfma_f32_16x16x32_bf16 v[102:105], v[192:195], v[222:225], v[102:105]
	v_mfma_f32_16x16x32_bf16 v[98:101], v[206:209], v[222:225], v[98:101]
	v_mfma_f32_16x16x32_bf16 v[86:89], v[192:195], v[230:233], v[86:89]
	v_mfma_f32_16x16x32_bf16 v[82:85], v[206:209], v[230:233], v[82:85]
	v_mfma_f32_16x16x32_bf16 v[70:73], v[192:195], v[238:241], v[70:73]
	v_mfma_f32_16x16x32_bf16 v[66:69], v[206:209], v[238:241], v[66:69]
	v_mfma_f32_16x16x32_bf16 v[118:121], v[202:205], v[218:221], v[118:121]
	v_mfma_f32_16x16x32_bf16 v[114:117], v[210:213], v[218:221], v[114:117]
	v_mfma_f32_16x16x32_bf16 v[102:105], v[202:205], v[226:229], v[102:105]
	v_mfma_f32_16x16x32_bf16 v[98:101], v[210:213], v[226:229], v[98:101]
	v_mfma_f32_16x16x32_bf16 v[86:89], v[202:205], v[234:237], v[86:89]
	v_mfma_f32_16x16x32_bf16 v[82:85], v[210:213], v[234:237], v[82:85]
	v_mfma_f32_16x16x32_bf16 v[70:73], v[202:205], v[242:245], v[70:73]
	v_mfma_f32_16x16x32_bf16 v[66:69], v[210:213], v[242:245], v[66:69]
	s_barrier
; #define PG8_STAGE(bufoff, gbase, voff) do { _Pragma("unroll") for (int _i = 0; _i < 2; ++_i) \
;         __builtin_amdgcn_global_load_lds((const unsigned*)((const char*)(gbase) + (voff)[_i]), (PG8_LAS unsigned*)(lds + (bufoff) + ldsw + _i * 8192), 16, 0, 0); } while (0)
; #define PG8_LDA(dst, b, h) do { _Pragma("unroll") for (int m = 0; m < 4; ++m) _Pragma("unroll") for (int k = 0; k < 2; ++k) dst[m][k] = *(const PG8_LAS bf16x8*)(lds + PG8_SA(b, h) + aoff + m * 2048 + k * 1024); } while (0)
; #define PG8_WAIT_V(n) asm volatile("s_waitcnt vmcnt(" #n ")" ::: "memory")
; template <class Epi, class Sched, bool ALIGN_EPI = false, bool SP2 = false>
; __device__ __forceinline__ void gemm_phase(PG8_LAS unsigned char* lds, const Gemm g, const Sched& S, const Epi& E) {
;     ...
;             PG8_LDA(At, 1, 1); PG8_STAGE(PG8_SB(1, 0), b3, voffB); PG8_STAGE(PG8_SB(1, 1), b3 + hstep, voffB); PG8_STAGE(PG8_SA(1, 0), a3, voffA);
;             PG8_WAIT_V(8); PG8_WAIT_L(0); PG8_BAR; PG8_MMA(1, 0, At, B0); PG8_MMA(1, 1, At, B1); PG8_BAR; PG8_SCHED;
;             } else {
;             PG8_LDB(B0, 0, 0); PG8_SCHED; PG8_LDA(At, 0, 0); PG8_STAGE(PG8_SA(1, 1), a1 + hstep, voffA);
;             PG8_WAIT_L(8); PG8_BAR; PG8_WAIT_L(0); PG8_MMA(0, 0, At, B0); PG8_BAR; PG8_SCHED;
;             PG8_LDB(B1, 0, 1); PG8_STAGE(PG8_SB(0, 0), b2, voffB);
;             PG8_BAR; PG8_WAIT_L(0); PG8_MMA(0, 1, At, B1); PG8_BAR;
;             PG8_LDA(At, 0, 1); PG8_STAGE(PG8_SA(0, 0), a2, voffA);
;             PG8_BAR; PG8_WAIT_L(0); PG8_MMA(1, 0, At, B0); PG8_BAR; PG8_SCHED;
;             PG8_STAGE(PG8_SB(0, 1), b2 + hstep, voffB);
;             PG8_WAIT_V(6); PG8_BAR; PG8_MMA(1, 1, At, B1); PG8_BAR;
;             PG8_LDB(B0, 1, 0); PG8_SCHED; PG8_LDA(At, 1, 0); PG8_STAGE(PG8_SA(0, 1), a2 + hstep, voffA);
;             PG8_WAIT_L(8); PG8_BAR; PG8_WAIT_L(0); PG8_MMA(0, 0, At, B0); PG8_BAR; PG8_SCHED;
;             PG8_LDB(B1, 1, 1); PG8_STAGE(PG8_SB(1, 0), b3, voffB);
;             PG8_BAR; PG8_WAIT_L(0); PG8_MMA(0, 1, At, B1); PG8_BAR;
;             PG8_LDA(At, 1, 1); PG8_STAGE(PG8_SA(1, 0), a3, voffA);
;             PG8_BAR; PG8_WAIT_L(0); PG8_MMA(1, 0, At, B0); PG8_BAR; PG8_SCHED;
;             PG8_STAGE(PG8_SB(1, 1), b3 + hstep, voffB);
;             PG8_WAIT_V(6); PG8_BAR; PG8_MMA(1, 1, At, B1); PG8_BAR;
;             }
;         }
;         if constexpr (ALIGN_EPI) { if (wr == 0) PG8_BAR; }
	s_add_i32 s2, s43, s26
	v_lshl_add_u64 v[152:153], v[152:153], 0, s[46:47]
	s_mov_b32 m0, s2
	ds_read_b128 v[214:217], v157 offset:49152
	ds_read_b128 v[218:221], v157 offset:50176
	ds_read_b128 v[222:225], v157 offset:51200
	ds_read_b128 v[226:229], v157 offset:52224
	ds_read_b128 v[230:233], v157 offset:53248
	ds_read_b128 v[234:237], v157 offset:54272
	ds_read_b128 v[238:241], v157 offset:55296
	ds_read_b128 v[242:245], v157 offset:56320
	global_load_lds_dwordx4 v[152:153], off
	s_add_i32 m0, s2, 0x2000
	s_add_u32 s2, s22, 0x40080
	v_lshl_add_u64 v[152:153], v[166:167], 0, s[46:47]
	s_addc_u32 s3, s23, 0
	s_add_i32 s22, s44, s26
	global_load_lds_dwordx4 v[152:153], off
	v_lshl_add_u64 v[152:153], s[2:3], 0, v[0:1]
	s_mov_b32 m0, s22
	s_nop 0
	global_load_lds_dwordx4 v[152:153], off
	v_lshl_add_u64 v[152:153], s[2:3], 0, v[138:139]
	s_add_i32 m0, s22, 0x2000
	s_nop 0
	global_load_lds_dwordx4 v[152:153], off
	v_lshl_add_u64 v[152:153], v[196:197], 0, s[46:47]
	s_mov_b32 m0, s31
	s_nop 0
	global_load_lds_dwordx4 v[152:153], off
	v_lshl_add_u64 v[152:153], v[246:247], 0, s[46:47]
	s_mov_b32 m0, s34
	s_nop 0
	global_load_lds_dwordx4 v[152:153], off
	s_waitcnt vmcnt(8)
	s_waitcnt lgkmcnt(0)
	s_barrier
	s_waitcnt lgkmcnt(0)
	v_mfma_f32_16x16x32_bf16 v[62:65], v[148:151], v[214:217], v[62:65]
	v_mfma_f32_16x16x32_bf16 v[58:61], v[162:165], v[214:217], v[58:61]
	v_mfma_f32_16x16x32_bf16 v[46:49], v[148:151], v[222:225], v[46:49]
	v_mfma_f32_16x16x32_bf16 v[42:45], v[162:165], v[222:225], v[42:45]
	v_mfma_f32_16x16x32_bf16 v[30:33], v[148:151], v[230:233], v[30:33]
	v_mfma_f32_16x16x32_bf16 v[26:29], v[162:165], v[230:233], v[26:29]
	v_mfma_f32_16x16x32_bf16 v[14:17], v[148:151], v[238:241], v[14:17]
	v_mfma_f32_16x16x32_bf16 v[10:13], v[162:165], v[238:241], v[10:13]
	v_mfma_f32_16x16x32_bf16 v[62:65], v[158:161], v[218:221], v[62:65]
	v_mfma_f32_16x16x32_bf16 v[58:61], v[188:191], v[218:221], v[58:61]
	v_mfma_f32_16x16x32_bf16 v[46:49], v[158:161], v[226:229], v[46:49]
	v_mfma_f32_16x16x32_bf16 v[42:45], v[188:191], v[226:229], v[42:45]
	v_mfma_f32_16x16x32_bf16 v[30:33], v[158:161], v[234:237], v[30:33]
	v_mfma_f32_16x16x32_bf16 v[26:29], v[188:191], v[234:237], v[26:29]
	v_mfma_f32_16x16x32_bf16 v[14:17], v[158:161], v[242:245], v[14:17]
	v_mfma_f32_16x16x32_bf16 v[10:13], v[188:191], v[242:245], v[10:13]
	v_mfma_f32_16x16x32_bf16 v[54:57], v[192:195], v[214:217], v[54:57]
	v_mfma_f32_16x16x32_bf16 v[50:53], v[206:209], v[214:217], v[50:53]
	v_mfma_f32_16x16x32_bf16 v[38:41], v[192:195], v[222:225], v[38:41]
	v_mfma_f32_16x16x32_bf16 v[34:37], v[206:209], v[222:225], v[34:37]
	v_mfma_f32_16x16x32_bf16 v[22:25], v[192:195], v[230:233], v[22:25]
	v_mfma_f32_16x16x32_bf16 v[18:21], v[206:209], v[230:233], v[18:21]
	v_mfma_f32_16x16x32_bf16 v[6:9], v[192:195], v[238:241], v[6:9]
	v_mfma_f32_16x16x32_bf16 v[2:5], v[206:209], v[238:241], v[2:5]
	v_mfma_f32_16x16x32_bf16 v[54:57], v[202:205], v[218:221], v[54:57]
	v_mfma_f32_16x16x32_bf16 v[50:53], v[210:213], v[218:221], v[50:53]
	v_mfma_f32_16x16x32_bf16 v[38:41], v[202:205], v[226:229], v[38:41]
	v_mfma_f32_16x16x32_bf16 v[34:37], v[210:213], v[226:229], v[34:37]
	v_mfma_f32_16x16x32_bf16 v[22:25], v[202:205], v[234:237], v[22:25]
	v_mfma_f32_16x16x32_bf16 v[18:21], v[210:213], v[234:237], v[18:21]
	v_mfma_f32_16x16x32_bf16 v[6:9], v[202:205], v[242:245], v[6:9]
	v_mfma_f32_16x16x32_bf16 v[2:5], v[210:213], v[242:245], v[2:5]
	s_barrier
	s_add_i32 s42, s42, 2
	s_add_u32 s20, s20, 0x100
	s_addc_u32 s21, s21, 0
	s_add_u32 s40, s40, 0x100
	s_addc_u32 s41, s41, 0
	s_cmp_gt_u32 s42, 13
	s_cbranch_scc0 .LBB0_90
	s_and_b64 vcc, exec, s[10:11]
	s_cbranch_vccz .LBB0_93
	s_barrier

; #define PG8_STAGE(bufoff, gbase, voff) do { _Pragma("unroll") for (int _i = 0; _i < 2; ++_i) \
;         __builtin_amdgcn_global_load_lds((const unsigned*)((const char*)(gbase) + (voff)[_i]), (PG8_LAS unsigned*)(lds + (bufoff) + ldsw + _i * 8192), 16, 0, 0); } while (0)
; #define PG8_LDA(dst, b, h) do { _Pragma("unroll") for (int m = 0; m < 4; ++m) _Pragma("unroll") for (int k = 0; k < 2; ++k) dst[m][k] = *(const PG8_LAS bf16x8*)(lds + PG8_SA(b, h) + aoff + m * 2048 + k * 1024); } while (0)
; #define PG8_LDB(dst, b, h) do { _Pragma("unroll") for (int n = 0; n < 2; ++n) _Pragma("unroll") for (int k = 0; k < 2; ++k) dst[n][k] = *(const PG8_LAS bf16x8*)(lds + PG8_SB(b, h) + boff + n * 2048 + k * 1024); } while (0)
; #define PG8_MMA(ai, bj, At, Bt) do { __builtin_amdgcn_s_setprio(1); _Pragma("unroll") for (int m = 0; m < 4; ++m) _Pragma("unroll") for (int n = 0; n < 2; ++n) _Pragma("unroll") for (int k = 0; k < 2; ++k) \
;         acc[ai][bj][m][n] = __builtin_amdgcn_mfma_f32_16x16x32_bf16(Bt[n][k], At[m][k], acc[ai][bj][m][n], 0, 0, 0); __builtin_amdgcn_s_setprio(0); } while (0)
; #define PG8_WAIT_V(n) asm volatile("s_waitcnt vmcnt(" #n ")" ::: "memory")
; #define PG8_WAIT_L(n) asm volatile("s_waitcnt lgkmcnt(" #n ")" ::: "memory")
; #define PG8_BAR __builtin_amdgcn_s_barrier()
; #define PG8_SCHED __builtin_amdgcn_sched_barrier(0)
; template <class Epi, class Sched, bool ALIGN_EPI = false, bool SP2 = false>
; __device__ __forceinline__ void gemm_phase(PG8_LAS unsigned char* lds, const Gemm g, const Sched& S, const Epi& E) {
;     ...
;             if constexpr (SP2) {
;             PG8_LDB(B0, 0, 0); PG8_LDB(B1, 0, 1); PG8_SCHED; PG8_LDA(At, 0, 0); PG8_STAGE(PG8_SA(1, 1), a1 + hstep, voffA);
;             PG8_WAIT_V(8); PG8_WAIT_L(0); PG8_BAR; PG8_MMA(0, 0, At, B0); PG8_MMA(0, 1, At, B1); PG8_BAR; PG8_SCHED;
;             PG8_LDA(At, 0, 1); PG8_STAGE(PG8_SB(0, 0), b2, voffB); PG8_STAGE(PG8_SB(0, 1), b2 + hstep, voffB); PG8_STAGE(PG8_SA(0, 0), a2, voffA);
;             PG8_WAIT_V(8); PG8_WAIT_L(0); PG8_BAR; PG8_MMA(1, 0, At, B0); PG8_MMA(1, 1, At, B1); PG8_BAR; PG8_SCHED;
.LBB0_108:
	s_add_u32 s2, s18, 0xfffc0080
	s_addc_u32 s3, s19, -1
	s_add_i32 s41, 0, 0x10000
	s_cmp_eq_u32 s40, 12
	s_cselect_b32 s23, s13, s3
	s_cselect_b32 s22, s36, s2
	s_cselect_b32 s21, s11, s39
	s_cselect_b32 s20, s37, s38
	s_add_i32 s42, 0, 0x14000
	v_add_u32_e32 v164, s41, v157
	v_add_u32_e32 v196, s42, v157
	ds_read_b128 v[148:151], v164
	ds_read_b128 v[152:155], v164 offset:1024
	ds_read_b128 v[160:163], v164 offset:2048
	ds_read_b128 v[164:167], v164 offset:3072
	ds_read_b128 v[188:191], v196
	ds_read_b128 v[192:195], v196 offset:1024
	ds_read_b128 v[202:205], v196 offset:2048
	ds_read_b128 v[206:209], v196 offset:3072
	v_lshl_add_u64 v[196:197], s[18:19], 0, v[144:145]
	s_add_i32 m0, s25, 0xc000
	ds_read_b128 v[210:213], v159
	ds_read_b128 v[214:217], v159 offset:1024
	ds_read_b128 v[218:221], v159 offset:2048
	ds_read_b128 v[222:225], v159 offset:3072
	ds_read_b128 v[226:229], v159 offset:4096
	ds_read_b128 v[230:233], v159 offset:5120
	ds_read_b128 v[234:237], v159 offset:6144
	ds_read_b128 v[238:241], v159 offset:7168
	global_load_lds_dwordx4 v[196:197], off
	v_lshl_add_u64 v[196:197], s[18:19], 0, v[146:147]
	s_add_i32 m0, s25, 0xe000
	s_nop 0
	global_load_lds_dwordx4 v[196:197], off
	s_waitcnt vmcnt(8)
	s_waitcnt lgkmcnt(0)
	s_barrier
	s_waitcnt lgkmcnt(0)
	v_mfma_f32_16x16x32_bf16 v[126:129], v[148:151], v[210:213], v[126:129]
	v_mfma_f32_16x16x32_bf16 v[122:125], v[160:163], v[210:213], v[122:125]
	v_mfma_f32_16x16x32_bf16 v[110:113], v[148:151], v[218:221], v[110:113]
	v_mfma_f32_16x16x32_bf16 v[106:109], v[160:163], v[218:221], v[106:109]
	v_mfma_f32_16x16x32_bf16 v[94:97], v[148:151], v[226:229], v[94:97]
	v_mfma_f32_16x16x32_bf16 v[90:93], v[160:163], v[226:229], v[90:93]
	v_mfma_f32_16x16x32_bf16 v[78:81], v[148:151], v[234:237], v[78:81]
	v_mfma_f32_16x16x32_bf16 v[74:77], v[160:163], v[234:237], v[74:77]
	v_mfma_f32_16x16x32_bf16 v[126:129], v[152:155], v[214:217], v[126:129]
	v_mfma_f32_16x16x32_bf16 v[122:125], v[164:167], v[214:217], v[122:125]
	v_mfma_f32_16x16x32_bf16 v[110:113], v[152:155], v[222:225], v[110:113]
	v_mfma_f32_16x16x32_bf16 v[106:109], v[164:167], v[222:225], v[106:109]
	v_mfma_f32_16x16x32_bf16 v[94:97], v[152:155], v[230:233], v[94:97]
	v_mfma_f32_16x16x32_bf16 v[90:93], v[164:167], v[230:233], v[90:93]
	v_mfma_f32_16x16x32_bf16 v[78:81], v[152:155], v[238:241], v[78:81]
	v_mfma_f32_16x16x32_bf16 v[74:77], v[164:167], v[238:241], v[74:77]
	v_mfma_f32_16x16x32_bf16 v[118:121], v[188:191], v[210:213], v[118:121]
	v_mfma_f32_16x16x32_bf16 v[114:117], v[202:205], v[210:213], v[114:117]
	v_mfma_f32_16x16x32_bf16 v[102:105], v[188:191], v[218:221], v[102:105]
	v_mfma_f32_16x16x32_bf16 v[98:101], v[202:205], v[218:221], v[98:101]
	v_mfma_f32_16x16x32_bf16 v[86:89], v[188:191], v[226:229], v[86:89]
	v_mfma_f32_16x16x32_bf16 v[82:85], v[202:205], v[226:229], v[82:85]
	v_mfma_f32_16x16x32_bf16 v[70:73], v[188:191], v[234:237], v[70:73]
	v_mfma_f32_16x16x32_bf16 v[66:69], v[202:205], v[234:237], v[66:69]
	v_mfma_f32_16x16x32_bf16 v[118:121], v[192:195], v[214:217], v[118:121]
	v_mfma_f32_16x16x32_bf16 v[114:117], v[206:209], v[214:217], v[114:117]
	v_mfma_f32_16x16x32_bf16 v[102:105], v[192:195], v[222:225], v[102:105]
	v_mfma_f32_16x16x32_bf16 v[98:101], v[206:209], v[222:225], v[98:101]
	v_mfma_f32_16x16x32_bf16 v[86:89], v[192:195], v[230:233], v[86:89]
	v_mfma_f32_16x16x32_bf16 v[82:85], v[206:209], v[230:233], v[82:85]
	v_mfma_f32_16x16x32_bf16 v[70:73], v[192:195], v[238:241], v[70:73]
	v_mfma_f32_16x16x32_bf16 v[66:69], v[206:209], v[238:241], v[66:69]
	s_barrier
	s_add_i32 s2, s41, s24
	v_lshl_add_u64 v[196:197], s[20:21], 0, v[0:1]
	s_mov_b32 m0, s2
	ds_read_b128 v[210:213], v159 offset:16384
	ds_read_b128 v[214:217], v159 offset:17408
	ds_read_b128 v[218:221], v159 offset:18432
	ds_read_b128 v[222:225], v159 offset:19456
	ds_read_b128 v[226:229], v159 offset:20480
	ds_read_b128 v[230:233], v159 offset:21504
	ds_read_b128 v[234:237], v159 offset:22528
	ds_read_b128 v[238:241], v159 offset:23552
	global_load_lds_dwordx4 v[196:197], off
	s_add_i32 m0, s2, 0x2000
	s_add_u32 s2, s20, 0x40000
	v_lshl_add_u64 v[242:243], s[20:21], 0, v[138:139]
	s_addc_u32 s3, s21, 0
	s_add_i32 s41, s42, s24
	global_load_lds_dwordx4 v[242:243], off
	v_lshl_add_u64 v[244:245], s[2:3], 0, v[0:1]
	s_mov_b32 m0, s41
	v_lshl_add_u64 v[246:247], s[22:23], 0, v[140:141]
	global_load_lds_dwordx4 v[244:245], off
	v_lshl_add_u64 v[244:245], s[2:3], 0, v[138:139]
	s_add_i32 m0, s41, 0x2000
	s_nop 0
	global_load_lds_dwordx4 v[244:245], off
	v_lshl_add_u64 v[244:245], s[22:23], 0, v[142:143]
	s_mov_b32 m0, s25
	s_nop 0
	global_load_lds_dwordx4 v[244:245], off
	s_mov_b32 m0, s26
	s_nop 0
	global_load_lds_dwordx4 v[246:247], off
	s_waitcnt vmcnt(8)
	s_waitcnt lgkmcnt(0)
	s_barrier
; #define PG8_STAGE(bufoff, gbase, voff) do { _Pragma("unroll") for (int _i = 0; _i < 2; ++_i) \
;         __builtin_amdgcn_global_load_lds((const unsigned*)((const char*)(gbase) + (voff)[_i]), (PG8_LAS unsigned*)(lds + (bufoff) + ldsw + _i * 8192), 16, 0, 0); } while (0)
; #define PG8_LDA(dst, b, h) do { _Pragma("unroll") for (int m = 0; m < 4; ++m) _Pragma("unroll") for (int k = 0; k < 2; ++k) dst[m][k] = *(const PG8_LAS bf16x8*)(lds + PG8_SA(b, h) + aoff + m * 2048 + k * 1024); } while (0)
; #define PG8_LDB(dst, b, h) do { _Pragma("unroll") for (int n = 0; n < 2; ++n) _Pragma("unroll") for (int k = 0; k < 2; ++k) dst[n][k] = *(const PG8_LAS bf16x8*)(lds + PG8_SB(b, h) + boff + n * 2048 + k * 1024); } while (0)
; #define PG8_MMA(ai, bj, At, Bt) do { __builtin_amdgcn_s_setprio(1); _Pragma("unroll") for (int m = 0; m < 4; ++m) _Pragma("unroll") for (int n = 0; n < 2; ++n) _Pragma("unroll") for (int k = 0; k < 2; ++k) \
;         acc[ai][bj][m][n] = __builtin_amdgcn_mfma_f32_16x16x32_bf16(Bt[n][k], At[m][k], acc[ai][bj][m][n], 0, 0, 0); __builtin_amdgcn_s_setprio(0); } while (0)
; #define PG8_WAIT_V(n) asm volatile("s_waitcnt vmcnt(" #n ")" ::: "memory")
; #define PG8_WAIT_L(n) asm volatile("s_waitcnt lgkmcnt(" #n ")" ::: "memory")
; #define PG8_BAR __builtin_amdgcn_s_barrier()
; #define PG8_SCHED __builtin_amdgcn_sched_barrier(0)
; template <class Epi, class Sched, bool ALIGN_EPI = false, bool SP2 = false>
; __device__ __forceinline__ void gemm_phase(PG8_LAS unsigned char* lds, const Gemm g, const Sched& S, const Epi& E) {
;     ...
;             PG8_WAIT_V(8); PG8_WAIT_L(0); PG8_BAR; PG8_MMA(1, 0, At, B0); PG8_MMA(1, 1, At, B1); PG8_BAR; PG8_SCHED;
;             PG8_LDB(B0, 1, 0); PG8_LDB(B1, 1, 1); PG8_SCHED; PG8_LDA(At, 1, 0); PG8_STAGE(PG8_SA(0, 1), a2 + hstep, voffA);
;             PG8_WAIT_V(8); PG8_WAIT_L(0); PG8_BAR; PG8_MMA(0, 0, At, B0); PG8_MMA(0, 1, At, B1); PG8_BAR; PG8_SCHED;
	s_waitcnt lgkmcnt(0)
	v_mfma_f32_16x16x32_bf16 v[62:65], v[148:151], v[210:213], v[62:65]
	v_mfma_f32_16x16x32_bf16 v[58:61], v[160:163], v[210:213], v[58:61]
	v_mfma_f32_16x16x32_bf16 v[46:49], v[148:151], v[218:221], v[46:49]
	v_mfma_f32_16x16x32_bf16 v[42:45], v[160:163], v[218:221], v[42:45]
	v_mfma_f32_16x16x32_bf16 v[30:33], v[148:151], v[226:229], v[30:33]
	v_mfma_f32_16x16x32_bf16 v[26:29], v[160:163], v[226:229], v[26:29]
	v_mfma_f32_16x16x32_bf16 v[14:17], v[148:151], v[234:237], v[14:17]
	v_mfma_f32_16x16x32_bf16 v[10:13], v[160:163], v[234:237], v[10:13]
	v_mfma_f32_16x16x32_bf16 v[62:65], v[152:155], v[214:217], v[62:65]
	v_mfma_f32_16x16x32_bf16 v[58:61], v[164:167], v[214:217], v[58:61]
	v_mfma_f32_16x16x32_bf16 v[46:49], v[152:155], v[222:225], v[46:49]
	v_mfma_f32_16x16x32_bf16 v[42:45], v[164:167], v[222:225], v[42:45]
	v_mfma_f32_16x16x32_bf16 v[30:33], v[152:155], v[230:233], v[30:33]
	v_mfma_f32_16x16x32_bf16 v[26:29], v[164:167], v[230:233], v[26:29]
	v_mfma_f32_16x16x32_bf16 v[14:17], v[152:155], v[238:241], v[14:17]
	v_mfma_f32_16x16x32_bf16 v[10:13], v[164:167], v[238:241], v[10:13]
	v_mfma_f32_16x16x32_bf16 v[54:57], v[188:191], v[210:213], v[54:57]
	v_mfma_f32_16x16x32_bf16 v[50:53], v[202:205], v[210:213], v[50:53]
	v_mfma_f32_16x16x32_bf16 v[38:41], v[188:191], v[218:221], v[38:41]
	v_mfma_f32_16x16x32_bf16 v[34:37], v[202:205], v[218:221], v[34:37]
	v_mfma_f32_16x16x32_bf16 v[22:25], v[188:191], v[226:229], v[22:25]
	v_mfma_f32_16x16x32_bf16 v[18:21], v[202:205], v[226:229], v[18:21]
	v_mfma_f32_16x16x32_bf16 v[6:9], v[188:191], v[234:237], v[6:9]
	v_mfma_f32_16x16x32_bf16 v[2:5], v[202:205], v[234:237], v[2:5]
	v_mfma_f32_16x16x32_bf16 v[54:57], v[192:195], v[214:217], v[54:57]
	v_mfma_f32_16x16x32_bf16 v[50:53], v[206:209], v[214:217], v[50:53]
	v_mfma_f32_16x16x32_bf16 v[38:41], v[192:195], v[222:225], v[38:41]
	v_mfma_f32_16x16x32_bf16 v[34:37], v[206:209], v[222:225], v[34:37]
	v_mfma_f32_16x16x32_bf16 v[22:25], v[192:195], v[230:233], v[22:25]
	v_mfma_f32_16x16x32_bf16 v[18:21], v[206:209], v[230:233], v[18:21]
	v_mfma_f32_16x16x32_bf16 v[6:9], v[192:195], v[238:241], v[6:9]
	v_mfma_f32_16x16x32_bf16 v[2:5], v[206:209], v[238:241], v[2:5]
	s_barrier
	s_add_i32 s41, 0, 0x18000
	s_add_i32 s42, 0, 0x1c000
	v_add_u32_e32 v164, s41, v157
	v_add_u32_e32 v206, s42, v157
	ds_read_b128 v[148:151], v164
	ds_read_b128 v[152:155], v164 offset:1024
	ds_read_b128 v[160:163], v164 offset:2048
	ds_read_b128 v[164:167], v164 offset:3072
	ds_read_b128 v[188:191], v206
	ds_read_b128 v[192:195], v206 offset:1024
	ds_read_b128 v[202:205], v206 offset:2048
	ds_read_b128 v[206:209], v206 offset:3072
	s_add_u32 s2, s22, 0x40000
	s_addc_u32 s3, s23, 0
	s_mov_b32 m0, s27
	v_lshl_add_u64 v[248:249], s[2:3], 0, v[142:143]
	ds_read_b128 v[210:213], v159 offset:32768
	ds_read_b128 v[214:217], v159 offset:33792
	ds_read_b128 v[218:221], v159 offset:34816
	ds_read_b128 v[222:225], v159 offset:35840
	ds_read_b128 v[226:229], v159 offset:36864
	ds_read_b128 v[230:233], v159 offset:37888
	ds_read_b128 v[234:237], v159 offset:38912
	ds_read_b128 v[238:241], v159 offset:39936
	global_load_lds_dwordx4 v[248:249], off
	v_lshl_add_u64 v[248:249], s[2:3], 0, v[140:141]
	s_mov_b32 m0, s28
	s_nop 0
	global_load_lds_dwordx4 v[248:249], off
	s_waitcnt vmcnt(8)
	s_waitcnt lgkmcnt(0)
	s_barrier
	s_waitcnt lgkmcnt(0)
	v_mfma_f32_16x16x32_bf16 v[126:129], v[148:151], v[210:213], v[126:129]
	v_mfma_f32_16x16x32_bf16 v[122:125], v[160:163], v[210:213], v[122:125]
	v_mfma_f32_16x16x32_bf16 v[110:113], v[148:151], v[218:221], v[110:113]
	v_mfma_f32_16x16x32_bf16 v[106:109], v[160:163], v[218:221], v[106:109]
	v_mfma_f32_16x16x32_bf16 v[94:97], v[148:151], v[226:229], v[94:97]
	v_mfma_f32_16x16x32_bf16 v[90:93], v[160:163], v[226:229], v[90:93]
	v_mfma_f32_16x16x32_bf16 v[78:81], v[148:151], v[234:237], v[78:81]
	v_mfma_f32_16x16x32_bf16 v[74:77], v[160:163], v[234:237], v[74:77]
	v_mfma_f32_16x16x32_bf16 v[126:129], v[152:155], v[214:217], v[126:129]
	v_mfma_f32_16x16x32_bf16 v[122:125], v[164:167], v[214:217], v[122:125]
	v_mfma_f32_16x16x32_bf16 v[110:113], v[152:155], v[222:225], v[110:113]
	v_mfma_f32_16x16x32_bf16 v[106:109], v[164:167], v[222:225], v[106:109]
	v_mfma_f32_16x16x32_bf16 v[94:97], v[152:155], v[230:233], v[94:97]
	v_mfma_f32_16x16x32_bf16 v[90:93], v[164:167], v[230:233], v[90:93]
	v_mfma_f32_16x16x32_bf16 v[78:81], v[152:155], v[238:241], v[78:81]
	v_mfma_f32_16x16x32_bf16 v[74:77], v[164:167], v[238:241], v[74:77]
	v_mfma_f32_16x16x32_bf16 v[118:121], v[188:191], v[210:213], v[118:121]
	v_mfma_f32_16x16x32_bf16 v[114:117], v[202:205], v[210:213], v[114:117]
	v_mfma_f32_16x16x32_bf16 v[102:105], v[188:191], v[218:221], v[102:105]
	v_mfma_f32_16x16x32_bf16 v[98:101], v[202:205], v[218:221], v[98:101]
	v_mfma_f32_16x16x32_bf16 v[86:89], v[188:191], v[226:229], v[86:89]
	v_mfma_f32_16x16x32_bf16 v[82:85], v[202:205], v[226:229], v[82:85]
	v_mfma_f32_16x16x32_bf16 v[70:73], v[188:191], v[234:237], v[70:73]
	v_mfma_f32_16x16x32_bf16 v[66:69], v[202:205], v[234:237], v[66:69]
	v_mfma_f32_16x16x32_bf16 v[118:121], v[192:195], v[214:217], v[118:121]
	v_mfma_f32_16x16x32_bf16 v[114:117], v[206:209], v[214:217], v[114:117]
	v_mfma_f32_16x16x32_bf16 v[102:105], v[192:195], v[222:225], v[102:105]
	v_mfma_f32_16x16x32_bf16 v[98:101], v[206:209], v[222:225], v[98:101]
	v_mfma_f32_16x16x32_bf16 v[86:89], v[192:195], v[230:233], v[86:89]
	v_mfma_f32_16x16x32_bf16 v[82:85], v[206:209], v[230:233], v[82:85]
	v_mfma_f32_16x16x32_bf16 v[70:73], v[192:195], v[238:241], v[70:73]
	v_mfma_f32_16x16x32_bf16 v[66:69], v[206:209], v[238:241], v[66:69]
	s_barrier
; #define PG8_STAGE(bufoff, gbase, voff) do { _Pragma("unroll") for (int _i = 0; _i < 2; ++_i) \
;         __builtin_amdgcn_global_load_lds((const unsigned*)((const char*)(gbase) + (voff)[_i]), (PG8_LAS unsigned*)(lds + (bufoff) + ldsw + _i * 8192), 16, 0, 0); } while (0)
; #define PG8_LDA(dst, b, h) do { _Pragma("unroll") for (int m = 0; m < 4; ++m) _Pragma("unroll") for (int k = 0; k < 2; ++k) dst[m][k] = *(const PG8_LAS bf16x8*)(lds + PG8_SA(b, h) + aoff + m * 2048 + k * 1024); } while (0)
; #define PG8_MMA(ai, bj, At, Bt) do { __builtin_amdgcn_s_setprio(1); _Pragma("unroll") for (int m = 0; m < 4; ++m) _Pragma("unroll") for (int n = 0; n < 2; ++n) _Pragma("unroll") for (int k = 0; k < 2; ++k) \
;         acc[ai][bj][m][n] = __builtin_amdgcn_mfma_f32_16x16x32_bf16(Bt[n][k], At[m][k], acc[ai][bj][m][n], 0, 0, 0); __builtin_amdgcn_s_setprio(0); } while (0)
; #define PG8_WAIT_V(n) asm volatile("s_waitcnt vmcnt(" #n ")" ::: "memory")
; #define PG8_WAIT_L(n) asm volatile("s_waitcnt lgkmcnt(" #n ")" ::: "memory")
; #define PG8_BAR __builtin_amdgcn_s_barrier()
; #define PG8_SCHED __builtin_amdgcn_sched_barrier(0)
; template <class Epi, class Sched, bool ALIGN_EPI = false, bool SP2 = false>
; __device__ __forceinline__ void gemm_phase(PG8_LAS unsigned char* lds, const Gemm g, const Sched& S, const Epi& E) {
;     ...
;         for (int t = 0; t < nt; t += 2) {
;             const bool last = (t == nt - 2);
;             const char* a1 = cA + (size_t)(t + 1) * kstep;
;             const char* a2 = last ? nA : cA + (size_t)(t + 2) * kstep; const char* b2 = last ? nB : cB + (size_t)(t + 2) * kstep;
;     ...
;             PG8_LDA(At, 1, 1); PG8_STAGE(PG8_SB(1, 0), b3, voffB); PG8_STAGE(PG8_SB(1, 1), b3 + hstep, voffB); PG8_STAGE(PG8_SA(1, 0), a3, voffA);
;             PG8_WAIT_V(8); PG8_WAIT_L(0); PG8_BAR; PG8_MMA(1, 0, At, B0); PG8_MMA(1, 1, At, B1); PG8_BAR; PG8_SCHED;
	s_add_i32 s2, s41, s24
	v_lshl_add_u64 v[196:197], v[196:197], 0, s[44:45]
	s_mov_b32 m0, s2
	ds_read_b128 v[210:213], v159 offset:49152
	ds_read_b128 v[214:217], v159 offset:50176
	ds_read_b128 v[218:221], v159 offset:51200
	ds_read_b128 v[222:225], v159 offset:52224
	ds_read_b128 v[226:229], v159 offset:53248
	ds_read_b128 v[230:233], v159 offset:54272
	ds_read_b128 v[234:237], v159 offset:55296
	ds_read_b128 v[238:241], v159 offset:56320
	global_load_lds_dwordx4 v[196:197], off
	s_add_i32 m0, s2, 0x2000
	s_add_u32 s2, s20, 0x40080
	v_lshl_add_u64 v[196:197], v[242:243], 0, s[44:45]
	s_addc_u32 s3, s21, 0
	s_add_i32 s20, s42, s24
	global_load_lds_dwordx4 v[196:197], off
	v_lshl_add_u64 v[196:197], s[2:3], 0, v[0:1]
	s_mov_b32 m0, s20
	s_nop 0
	global_load_lds_dwordx4 v[196:197], off
	v_lshl_add_u64 v[196:197], s[2:3], 0, v[138:139]
	s_add_i32 m0, s20, 0x2000
	s_nop 0
	global_load_lds_dwordx4 v[196:197], off
	v_lshl_add_u64 v[196:197], v[244:245], 0, s[44:45]
	s_mov_b32 m0, s29
	s_nop 0
	global_load_lds_dwordx4 v[196:197], off
	v_lshl_add_u64 v[196:197], v[246:247], 0, s[44:45]
	s_mov_b32 m0, s30
	s_nop 0
	global_load_lds_dwordx4 v[196:197], off
	s_waitcnt vmcnt(8)
	s_waitcnt lgkmcnt(0)
	s_barrier
	s_waitcnt lgkmcnt(0)
	v_mfma_f32_16x16x32_bf16 v[62:65], v[148:151], v[210:213], v[62:65]
	v_mfma_f32_16x16x32_bf16 v[58:61], v[160:163], v[210:213], v[58:61]
	v_mfma_f32_16x16x32_bf16 v[46:49], v[148:151], v[218:221], v[46:49]
	v_mfma_f32_16x16x32_bf16 v[42:45], v[160:163], v[218:221], v[42:45]
	v_mfma_f32_16x16x32_bf16 v[30:33], v[148:151], v[226:229], v[30:33]
	v_mfma_f32_16x16x32_bf16 v[26:29], v[160:163], v[226:229], v[26:29]
	v_mfma_f32_16x16x32_bf16 v[14:17], v[148:151], v[234:237], v[14:17]
	v_mfma_f32_16x16x32_bf16 v[10:13], v[160:163], v[234:237], v[10:13]
	v_mfma_f32_16x16x32_bf16 v[62:65], v[152:155], v[214:217], v[62:65]
	v_mfma_f32_16x16x32_bf16 v[58:61], v[164:167], v[214:217], v[58:61]
	v_mfma_f32_16x16x32_bf16 v[46:49], v[152:155], v[222:225], v[46:49]
	v_mfma_f32_16x16x32_bf16 v[42:45], v[164:167], v[222:225], v[42:45]
	v_mfma_f32_16x16x32_bf16 v[30:33], v[152:155], v[230:233], v[30:33]
	v_mfma_f32_16x16x32_bf16 v[26:29], v[164:167], v[230:233], v[26:29]
	v_mfma_f32_16x16x32_bf16 v[14:17], v[152:155], v[238:241], v[14:17]
	v_mfma_f32_16x16x32_bf16 v[10:13], v[164:167], v[238:241], v[10:13]
	v_mfma_f32_16x16x32_bf16 v[54:57], v[188:191], v[210:213], v[54:57]
	v_mfma_f32_16x16x32_bf16 v[50:53], v[202:205], v[210:213], v[50:53]
	v_mfma_f32_16x16x32_bf16 v[38:41], v[188:191], v[218:221], v[38:41]
	v_mfma_f32_16x16x32_bf16 v[34:37], v[202:205], v[218:221], v[34:37]
	v_mfma_f32_16x16x32_bf16 v[22:25], v[188:191], v[226:229], v[22:25]
	v_mfma_f32_16x16x32_bf16 v[18:21], v[202:205], v[226:229], v[18:21]
	v_mfma_f32_16x16x32_bf16 v[6:9], v[188:191], v[234:237], v[6:9]
	v_mfma_f32_16x16x32_bf16 v[2:5], v[202:205], v[234:237], v[2:5]
	v_mfma_f32_16x16x32_bf16 v[54:57], v[192:195], v[214:217], v[54:57]
	v_mfma_f32_16x16x32_bf16 v[50:53], v[206:209], v[214:217], v[50:53]
	v_mfma_f32_16x16x32_bf16 v[38:41], v[192:195], v[222:225], v[38:41]
	v_mfma_f32_16x16x32_bf16 v[34:37], v[206:209], v[222:225], v[34:37]
	v_mfma_f32_16x16x32_bf16 v[22:25], v[192:195], v[230:233], v[22:25]
	v_mfma_f32_16x16x32_bf16 v[18:21], v[206:209], v[230:233], v[18:21]
	v_mfma_f32_16x16x32_bf16 v[6:9], v[192:195], v[238:241], v[6:9]
	v_mfma_f32_16x16x32_bf16 v[2:5], v[206:209], v[238:241], v[2:5]
	s_barrier
	s_add_i32 s40, s40, 2
	s_add_u32 s18, s18, 0x100
	s_addc_u32 s19, s19, 0
	s_add_u32 s38, s38, 0x100
	s_addc_u32 s39, s39, 0
	s_cmp_gt_u32 s40, 13
	s_cbranch_scc0 .LBB0_108
	s_and_b64 vcc, exec, s[8:9]
	s_cbranch_vccz .LBB0_111
	s_barrier

; #define PG8_STAGE(bufoff, gbase, voff) do { _Pragma("unroll") for (int _i = 0; _i < 2; ++_i) \
;         __builtin_amdgcn_global_load_lds((const unsigned*)((const char*)(gbase) + (voff)[_i]), (PG8_LAS unsigned*)(lds + (bufoff) + ldsw + _i * 8192), 16, 0, 0); } while (0)
; #define PG8_LDA(dst, b, h) do { _Pragma("unroll") for (int m = 0; m < 4; ++m) _Pragma("unroll") for (int k = 0; k < 2; ++k) dst[m][k] = *(const PG8_LAS bf16x8*)(lds + PG8_SA(b, h) + aoff + m * 2048 + k * 1024); } while (0)
; #define PG8_LDB(dst, b, h) do { _Pragma("unroll") for (int n = 0; n < 2; ++n) _Pragma("unroll") for (int k = 0; k < 2; ++k) dst[n][k] = *(const PG8_LAS bf16x8*)(lds + PG8_SB(b, h) + boff + n * 2048 + k * 1024); } while (0)
; #define PG8_MMA(ai, bj, At, Bt) do { __builtin_amdgcn_s_setprio(1); _Pragma("unroll") for (int m = 0; m < 4; ++m) _Pragma("unroll") for (int n = 0; n < 2; ++n) _Pragma("unroll") for (int k = 0; k < 2; ++k) \
;         acc[ai][bj][m][n] = __builtin_amdgcn_mfma_f32_16x16x32_bf16(Bt[n][k], At[m][k], acc[ai][bj][m][n], 0, 0, 0); __builtin_amdgcn_s_setprio(0); } while (0)
; #define PG8_WAIT_V(n) asm volatile("s_waitcnt vmcnt(" #n ")" ::: "memory")
; #define PG8_WAIT_L(n) asm volatile("s_waitcnt lgkmcnt(" #n ")" ::: "memory")
; #define PG8_BAR __builtin_amdgcn_s_barrier()
; #define PG8_SCHED __builtin_amdgcn_sched_barrier(0)
; template <class Epi, class Sched, bool ALIGN_EPI = false, bool SP2 = false>
; __device__ __forceinline__ void gemm_phase(PG8_LAS unsigned char* lds, const Gemm g, const Sched& S, const Epi& E) {
;     ...
;         for (int t = 0; t < nt; t += 2) {
;             const bool last = (t == nt - 2);
;             const char* a1 = cA + (size_t)(t + 1) * kstep;
;             const char* a2 = last ? nA : cA + (size_t)(t + 2) * kstep; const char* b2 = last ? nB : cB + (size_t)(t + 2) * kstep;
;             const char* a3 = a2 + kstep; const char* b3 = b2 + kstep;
;             if (last && has_next) S.a_ready(nxt);
;             if constexpr (SP2) {
;             PG8_LDB(B0, 0, 0); PG8_LDB(B1, 0, 1); PG8_SCHED; PG8_LDA(At, 0, 0); PG8_STAGE(PG8_SA(1, 1), a1 + hstep, voffA);
;             PG8_WAIT_V(8); PG8_WAIT_L(0); PG8_BAR; PG8_MMA(0, 0, At, B0); PG8_MMA(0, 1, At, B1); PG8_BAR; PG8_SCHED;
;             PG8_LDA(At, 0, 1); PG8_STAGE(PG8_SB(0, 0), b2, voffB); PG8_STAGE(PG8_SB(0, 1), b2 + hstep, voffB); PG8_STAGE(PG8_SA(0, 0), a2, voffA);
.LBB0_1025:
	s_add_u32 s2, s18, 0xfffc0080
	s_addc_u32 s3, s19, -1
	s_add_i32 s43, 0, 0x10000
	s_cmp_eq_u32 s42, 12
	s_cselect_b32 s23, s13, s3
	s_cselect_b32 s22, s38, s2
	v_add_u32_e32 v144, s43, v147
	s_cselect_b32 s21, s11, s41
	s_cselect_b32 s20, s39, s40
	s_add_i32 s44, 0, 0x14000
	ds_read_b128 v[150:153], v144
	ds_read_b128 v[154:157], v144 offset:1024
	ds_read_b128 v[158:161], v144 offset:2048
	ds_read_b128 v[162:165], v144 offset:3072
	v_add_u32_e32 v144, s44, v147
	ds_read_b128 v[188:191], v144
	ds_read_b128 v[192:195], v144 offset:1024
	ds_read_b128 v[202:205], v144 offset:2048
	ds_read_b128 v[206:209], v144 offset:3072
	v_lshl_add_u64 v[144:145], s[18:19], 0, v[140:141]
	s_add_i32 m0, s25, 0xc000
	ds_read_b128 v[210:213], v149
	ds_read_b128 v[214:217], v149 offset:1024
	ds_read_b128 v[218:221], v149 offset:2048
	ds_read_b128 v[222:225], v149 offset:3072
	ds_read_b128 v[226:229], v149 offset:4096
	ds_read_b128 v[230:233], v149 offset:5120
	ds_read_b128 v[234:237], v149 offset:6144
	ds_read_b128 v[238:241], v149 offset:7168
	global_load_lds_dwordx4 v[144:145], off
	v_lshl_add_u64 v[144:145], s[18:19], 0, v[142:143]
	s_add_i32 m0, s25, 0xe000
	s_nop 0
	global_load_lds_dwordx4 v[144:145], off
	s_waitcnt vmcnt(8)
	s_waitcnt lgkmcnt(0)
	s_barrier
	s_waitcnt lgkmcnt(0)
	v_mfma_f32_16x16x32_bf16 v[126:129], v[150:153], v[210:213], v[126:129]
	v_mfma_f32_16x16x32_bf16 v[122:125], v[158:161], v[210:213], v[122:125]
	v_mfma_f32_16x16x32_bf16 v[110:113], v[150:153], v[218:221], v[110:113]
	v_mfma_f32_16x16x32_bf16 v[106:109], v[158:161], v[218:221], v[106:109]
	v_mfma_f32_16x16x32_bf16 v[102:105], v[150:153], v[226:229], v[102:105]
	v_mfma_f32_16x16x32_bf16 v[98:101], v[158:161], v[226:229], v[98:101]
	v_mfma_f32_16x16x32_bf16 v[86:89], v[150:153], v[234:237], v[86:89]
	v_mfma_f32_16x16x32_bf16 v[82:85], v[158:161], v[234:237], v[82:85]
	v_mfma_f32_16x16x32_bf16 v[126:129], v[154:157], v[214:217], v[126:129]
	v_mfma_f32_16x16x32_bf16 v[122:125], v[162:165], v[214:217], v[122:125]
	v_mfma_f32_16x16x32_bf16 v[110:113], v[154:157], v[222:225], v[110:113]
	v_mfma_f32_16x16x32_bf16 v[106:109], v[162:165], v[222:225], v[106:109]
	v_mfma_f32_16x16x32_bf16 v[102:105], v[154:157], v[230:233], v[102:105]
	v_mfma_f32_16x16x32_bf16 v[98:101], v[162:165], v[230:233], v[98:101]
	v_mfma_f32_16x16x32_bf16 v[86:89], v[154:157], v[238:241], v[86:89]
	v_mfma_f32_16x16x32_bf16 v[82:85], v[162:165], v[238:241], v[82:85]
	v_mfma_f32_16x16x32_bf16 v[118:121], v[188:191], v[210:213], v[118:121]
	v_mfma_f32_16x16x32_bf16 v[114:117], v[202:205], v[210:213], v[114:117]
	v_mfma_f32_16x16x32_bf16 v[94:97], v[188:191], v[218:221], v[94:97]
	v_mfma_f32_16x16x32_bf16 v[90:93], v[202:205], v[218:221], v[90:93]
	v_mfma_f32_16x16x32_bf16 v[78:81], v[188:191], v[226:229], v[78:81]
	v_mfma_f32_16x16x32_bf16 v[74:77], v[202:205], v[226:229], v[74:77]
	v_mfma_f32_16x16x32_bf16 v[70:73], v[188:191], v[234:237], v[70:73]
	v_mfma_f32_16x16x32_bf16 v[66:69], v[202:205], v[234:237], v[66:69]
	v_mfma_f32_16x16x32_bf16 v[118:121], v[192:195], v[214:217], v[118:121]
	v_mfma_f32_16x16x32_bf16 v[114:117], v[206:209], v[214:217], v[114:117]
	v_mfma_f32_16x16x32_bf16 v[94:97], v[192:195], v[222:225], v[94:97]
	v_mfma_f32_16x16x32_bf16 v[90:93], v[206:209], v[222:225], v[90:93]
	v_mfma_f32_16x16x32_bf16 v[78:81], v[192:195], v[230:233], v[78:81]
	v_mfma_f32_16x16x32_bf16 v[74:77], v[206:209], v[230:233], v[74:77]
	v_mfma_f32_16x16x32_bf16 v[70:73], v[192:195], v[238:241], v[70:73]
	v_mfma_f32_16x16x32_bf16 v[66:69], v[206:209], v[238:241], v[66:69]
	s_barrier
	s_add_i32 s2, s43, s24
	v_lshl_add_u64 v[144:145], s[20:21], 0, v[0:1]
	s_mov_b32 m0, s2
	ds_read_b128 v[210:213], v149 offset:16384
	ds_read_b128 v[214:217], v149 offset:17408
	ds_read_b128 v[218:221], v149 offset:18432
	ds_read_b128 v[222:225], v149 offset:19456
	ds_read_b128 v[226:229], v149 offset:20480
	ds_read_b128 v[230:233], v149 offset:21504
	ds_read_b128 v[234:237], v149 offset:22528
	ds_read_b128 v[238:241], v149 offset:23552
	global_load_lds_dwordx4 v[144:145], off
	s_add_i32 m0, s2, 0x2000
	s_add_u32 s2, s20, 0x40000
	v_lshl_add_u64 v[166:167], s[20:21], 0, v[138:139]
	s_addc_u32 s3, s21, 0
	s_add_i32 s43, s44, s24
	global_load_lds_dwordx4 v[166:167], off
	v_lshl_add_u64 v[196:197], s[2:3], 0, v[0:1]
	s_mov_b32 m0, s43
	v_lshl_add_u64 v[242:243], s[22:23], 0, v[138:139]
	global_load_lds_dwordx4 v[196:197], off
	v_lshl_add_u64 v[196:197], s[2:3], 0, v[138:139]
	s_add_i32 m0, s43, 0x2000
	s_nop 0
	global_load_lds_dwordx4 v[196:197], off
	v_lshl_add_u64 v[196:197], s[22:23], 0, v[0:1]
	s_mov_b32 m0, s25
	s_nop 0
	global_load_lds_dwordx4 v[196:197], off
	s_mov_b32 m0, s28
	s_nop 0
	global_load_lds_dwordx4 v[242:243], off
	s_waitcnt vmcnt(8)
	s_waitcnt lgkmcnt(0)
	s_barrier
; #define PG8_STAGE(bufoff, gbase, voff) do { _Pragma("unroll") for (int _i = 0; _i < 2; ++_i) \
;         __builtin_amdgcn_global_load_lds((const unsigned*)((const char*)(gbase) + (voff)[_i]), (PG8_LAS unsigned*)(lds + (bufoff) + ldsw + _i * 8192), 16, 0, 0); } while (0)
; #define PG8_LDA(dst, b, h) do { _Pragma("unroll") for (int m = 0; m < 4; ++m) _Pragma("unroll") for (int k = 0; k < 2; ++k) dst[m][k] = *(const PG8_LAS bf16x8*)(lds + PG8_SA(b, h) + aoff + m * 2048 + k * 1024); } while (0)
; #define PG8_LDB(dst, b, h) do { _Pragma("unroll") for (int n = 0; n < 2; ++n) _Pragma("unroll") for (int k = 0; k < 2; ++k) dst[n][k] = *(const PG8_LAS bf16x8*)(lds + PG8_SB(b, h) + boff + n * 2048 + k * 1024); } while (0)
; #define PG8_MMA(ai, bj, At, Bt) do { __builtin_amdgcn_s_setprio(1); _Pragma("unroll") for (int m = 0; m < 4; ++m) _Pragma("unroll") for (int n = 0; n < 2; ++n) _Pragma("unroll") for (int k = 0; k < 2; ++k) \
;         acc[ai][bj][m][n] = __builtin_amdgcn_mfma_f32_16x16x32_bf16(Bt[n][k], At[m][k], acc[ai][bj][m][n], 0, 0, 0); __builtin_amdgcn_s_setprio(0); } while (0)
; #define PG8_WAIT_V(n) asm volatile("s_waitcnt vmcnt(" #n ")" ::: "memory")
; #define PG8_WAIT_L(n) asm volatile("s_waitcnt lgkmcnt(" #n ")" ::: "memory")
; #define PG8_BAR __builtin_amdgcn_s_barrier()
; #define PG8_SCHED __builtin_amdgcn_sched_barrier(0)
; template <class Epi, class Sched, bool ALIGN_EPI = false, bool SP2 = false>
; __device__ __forceinline__ void gemm_phase(PG8_LAS unsigned char* lds, const Gemm g, const Sched& S, const Epi& E) {
;     ...
;             PG8_WAIT_V(8); PG8_WAIT_L(0); PG8_BAR; PG8_MMA(1, 0, At, B0); PG8_MMA(1, 1, At, B1); PG8_BAR; PG8_SCHED;
;             PG8_LDB(B0, 1, 0); PG8_LDB(B1, 1, 1); PG8_SCHED; PG8_LDA(At, 1, 0); PG8_STAGE(PG8_SA(0, 1), a2 + hstep, voffA);
;             PG8_WAIT_V(8); PG8_WAIT_L(0); PG8_BAR; PG8_MMA(0, 0, At, B0); PG8_MMA(0, 1, At, B1); PG8_BAR; PG8_SCHED;
	s_waitcnt lgkmcnt(0)
	v_mfma_f32_16x16x32_bf16 v[62:65], v[150:153], v[210:213], v[62:65]
	v_mfma_f32_16x16x32_bf16 v[58:61], v[158:161], v[210:213], v[58:61]
	v_mfma_f32_16x16x32_bf16 v[46:49], v[150:153], v[218:221], v[46:49]
	v_mfma_f32_16x16x32_bf16 v[42:45], v[158:161], v[218:221], v[42:45]
	v_mfma_f32_16x16x32_bf16 v[30:33], v[150:153], v[226:229], v[30:33]
	v_mfma_f32_16x16x32_bf16 v[26:29], v[158:161], v[226:229], v[26:29]
	v_mfma_f32_16x16x32_bf16 v[14:17], v[150:153], v[234:237], v[14:17]
	v_mfma_f32_16x16x32_bf16 v[10:13], v[158:161], v[234:237], v[10:13]
	v_mfma_f32_16x16x32_bf16 v[62:65], v[154:157], v[214:217], v[62:65]
	v_mfma_f32_16x16x32_bf16 v[58:61], v[162:165], v[214:217], v[58:61]
	v_mfma_f32_16x16x32_bf16 v[46:49], v[154:157], v[222:225], v[46:49]
	v_mfma_f32_16x16x32_bf16 v[42:45], v[162:165], v[222:225], v[42:45]
	v_mfma_f32_16x16x32_bf16 v[30:33], v[154:157], v[230:233], v[30:33]
	v_mfma_f32_16x16x32_bf16 v[26:29], v[162:165], v[230:233], v[26:29]
	v_mfma_f32_16x16x32_bf16 v[14:17], v[154:157], v[238:241], v[14:17]
	v_mfma_f32_16x16x32_bf16 v[10:13], v[162:165], v[238:241], v[10:13]
	v_mfma_f32_16x16x32_bf16 v[54:57], v[188:191], v[210:213], v[54:57]
	v_mfma_f32_16x16x32_bf16 v[50:53], v[202:205], v[210:213], v[50:53]
	v_mfma_f32_16x16x32_bf16 v[38:41], v[188:191], v[218:221], v[38:41]
	v_mfma_f32_16x16x32_bf16 v[34:37], v[202:205], v[218:221], v[34:37]
	v_mfma_f32_16x16x32_bf16 v[22:25], v[188:191], v[226:229], v[22:25]
	v_mfma_f32_16x16x32_bf16 v[18:21], v[202:205], v[226:229], v[18:21]
	v_mfma_f32_16x16x32_bf16 v[6:9], v[188:191], v[234:237], v[6:9]
	v_mfma_f32_16x16x32_bf16 v[2:5], v[202:205], v[234:237], v[2:5]
	v_mfma_f32_16x16x32_bf16 v[54:57], v[192:195], v[214:217], v[54:57]
	v_mfma_f32_16x16x32_bf16 v[50:53], v[206:209], v[214:217], v[50:53]
	v_mfma_f32_16x16x32_bf16 v[38:41], v[192:195], v[222:225], v[38:41]
	v_mfma_f32_16x16x32_bf16 v[34:37], v[206:209], v[222:225], v[34:37]
	v_mfma_f32_16x16x32_bf16 v[22:25], v[192:195], v[230:233], v[22:25]
	v_mfma_f32_16x16x32_bf16 v[18:21], v[206:209], v[230:233], v[18:21]
	v_mfma_f32_16x16x32_bf16 v[6:9], v[192:195], v[238:241], v[6:9]
	v_mfma_f32_16x16x32_bf16 v[2:5], v[206:209], v[238:241], v[2:5]
	s_barrier
	s_add_i32 s43, 0, 0x18000
	s_add_i32 s44, 0, 0x1c000
	v_add_u32_e32 v162, s43, v147
	v_add_u32_e32 v206, s44, v147
	ds_read_b128 v[150:153], v162
	ds_read_b128 v[154:157], v162 offset:1024
	ds_read_b128 v[158:161], v162 offset:2048
	ds_read_b128 v[162:165], v162 offset:3072
	ds_read_b128 v[188:191], v206
	ds_read_b128 v[192:195], v206 offset:1024
	ds_read_b128 v[202:205], v206 offset:2048
	ds_read_b128 v[206:209], v206 offset:3072
	s_add_u32 s2, s22, 0x40000
	s_addc_u32 s3, s23, 0
	s_mov_b32 m0, s29
	v_lshl_add_u64 v[244:245], s[2:3], 0, v[0:1]
	ds_read_b128 v[210:213], v149 offset:32768
	ds_read_b128 v[214:217], v149 offset:33792
	ds_read_b128 v[218:221], v149 offset:34816
	ds_read_b128 v[222:225], v149 offset:35840
	ds_read_b128 v[226:229], v149 offset:36864
	ds_read_b128 v[230:233], v149 offset:37888
	ds_read_b128 v[234:237], v149 offset:38912
	ds_read_b128 v[238:241], v149 offset:39936
	global_load_lds_dwordx4 v[244:245], off
	v_lshl_add_u64 v[244:245], s[2:3], 0, v[138:139]
	s_mov_b32 m0, s30
	s_nop 0
	global_load_lds_dwordx4 v[244:245], off
	s_waitcnt vmcnt(8)
	s_waitcnt lgkmcnt(0)
	s_barrier
	s_waitcnt lgkmcnt(0)
	v_mfma_f32_16x16x32_bf16 v[126:129], v[150:153], v[210:213], v[126:129]
	v_mfma_f32_16x16x32_bf16 v[122:125], v[158:161], v[210:213], v[122:125]
	v_mfma_f32_16x16x32_bf16 v[110:113], v[150:153], v[218:221], v[110:113]
	v_mfma_f32_16x16x32_bf16 v[106:109], v[158:161], v[218:221], v[106:109]
	v_mfma_f32_16x16x32_bf16 v[102:105], v[150:153], v[226:229], v[102:105]
	v_mfma_f32_16x16x32_bf16 v[98:101], v[158:161], v[226:229], v[98:101]
	v_mfma_f32_16x16x32_bf16 v[86:89], v[150:153], v[234:237], v[86:89]
	v_mfma_f32_16x16x32_bf16 v[82:85], v[158:161], v[234:237], v[82:85]
	v_mfma_f32_16x16x32_bf16 v[126:129], v[154:157], v[214:217], v[126:129]
	v_mfma_f32_16x16x32_bf16 v[122:125], v[162:165], v[214:217], v[122:125]
	v_mfma_f32_16x16x32_bf16 v[110:113], v[154:157], v[222:225], v[110:113]
	v_mfma_f32_16x16x32_bf16 v[106:109], v[162:165], v[222:225], v[106:109]
	v_mfma_f32_16x16x32_bf16 v[102:105], v[154:157], v[230:233], v[102:105]
	v_mfma_f32_16x16x32_bf16 v[98:101], v[162:165], v[230:233], v[98:101]
	v_mfma_f32_16x16x32_bf16 v[86:89], v[154:157], v[238:241], v[86:89]
	v_mfma_f32_16x16x32_bf16 v[82:85], v[162:165], v[238:241], v[82:85]
	v_mfma_f32_16x16x32_bf16 v[118:121], v[188:191], v[210:213], v[118:121]
	v_mfma_f32_16x16x32_bf16 v[114:117], v[202:205], v[210:213], v[114:117]
	v_mfma_f32_16x16x32_bf16 v[94:97], v[188:191], v[218:221], v[94:97]
	v_mfma_f32_16x16x32_bf16 v[90:93], v[202:205], v[218:221], v[90:93]
	v_mfma_f32_16x16x32_bf16 v[78:81], v[188:191], v[226:229], v[78:81]
	v_mfma_f32_16x16x32_bf16 v[74:77], v[202:205], v[226:229], v[74:77]
	v_mfma_f32_16x16x32_bf16 v[70:73], v[188:191], v[234:237], v[70:73]
	v_mfma_f32_16x16x32_bf16 v[66:69], v[202:205], v[234:237], v[66:69]
	v_mfma_f32_16x16x32_bf16 v[118:121], v[192:195], v[214:217], v[118:121]
	v_mfma_f32_16x16x32_bf16 v[114:117], v[206:209], v[214:217], v[114:117]
	v_mfma_f32_16x16x32_bf16 v[94:97], v[192:195], v[222:225], v[94:97]
	v_mfma_f32_16x16x32_bf16 v[90:93], v[206:209], v[222:225], v[90:93]
	v_mfma_f32_16x16x32_bf16 v[78:81], v[192:195], v[230:233], v[78:81]
	v_mfma_f32_16x16x32_bf16 v[74:77], v[206:209], v[230:233], v[74:77]
	v_mfma_f32_16x16x32_bf16 v[70:73], v[192:195], v[238:241], v[70:73]
	v_mfma_f32_16x16x32_bf16 v[66:69], v[206:209], v[238:241], v[66:69]
	s_barrier
; #define PG8_STAGE(bufoff, gbase, voff) do { _Pragma("unroll") for (int _i = 0; _i < 2; ++_i) \
;         __builtin_amdgcn_global_load_lds((const unsigned*)((const char*)(gbase) + (voff)[_i]), (PG8_LAS unsigned*)(lds + (bufoff) + ldsw + _i * 8192), 16, 0, 0); } while (0)
; #define PG8_LDA(dst, b, h) do { _Pragma("unroll") for (int m = 0; m < 4; ++m) _Pragma("unroll") for (int k = 0; k < 2; ++k) dst[m][k] = *(const PG8_LAS bf16x8*)(lds + PG8_SA(b, h) + aoff + m * 2048 + k * 1024); } while (0)
; #define PG8_MMA(ai, bj, At, Bt) do { __builtin_amdgcn_s_setprio(1); _Pragma("unroll") for (int m = 0; m < 4; ++m) _Pragma("unroll") for (int n = 0; n < 2; ++n) _Pragma("unroll") for (int k = 0; k < 2; ++k) \
;         acc[ai][bj][m][n] = __builtin_amdgcn_mfma_f32_16x16x32_bf16(Bt[n][k], At[m][k], acc[ai][bj][m][n], 0, 0, 0); __builtin_amdgcn_s_setprio(0); } while (0)
; #define PG8_WAIT_V(n) asm volatile("s_waitcnt vmcnt(" #n ")" ::: "memory")
; #define PG8_WAIT_L(n) asm volatile("s_waitcnt lgkmcnt(" #n ")" ::: "memory")
; #define PG8_BAR __builtin_amdgcn_s_barrier()
; #define PG8_SCHED __builtin_amdgcn_sched_barrier(0)
; template <class Epi, class Sched, bool ALIGN_EPI = false, bool SP2 = false>
; __device__ __forceinline__ void gemm_phase(PG8_LAS unsigned char* lds, const Gemm g, const Sched& S, const Epi& E) {
;     ...
;             PG8_LDA(At, 1, 1); PG8_STAGE(PG8_SB(1, 0), b3, voffB); PG8_STAGE(PG8_SB(1, 1), b3 + hstep, voffB); PG8_STAGE(PG8_SA(1, 0), a3, voffA);
;             PG8_WAIT_V(8); PG8_WAIT_L(0); PG8_BAR; PG8_MMA(1, 0, At, B0); PG8_MMA(1, 1, At, B1); PG8_BAR; PG8_SCHED;
	s_add_i32 s2, s43, s24
	v_lshl_add_u64 v[144:145], v[144:145], 0, s[46:47]
	s_mov_b32 m0, s2
	ds_read_b128 v[210:213], v149 offset:49152
	ds_read_b128 v[214:217], v149 offset:50176
	ds_read_b128 v[218:221], v149 offset:51200
	ds_read_b128 v[222:225], v149 offset:52224
	ds_read_b128 v[226:229], v149 offset:53248
	ds_read_b128 v[230:233], v149 offset:54272
	ds_read_b128 v[234:237], v149 offset:55296
	ds_read_b128 v[238:241], v149 offset:56320
	global_load_lds_dwordx4 v[144:145], off
	s_add_i32 m0, s2, 0x2000
	s_add_u32 s2, s20, 0x40080
	v_lshl_add_u64 v[144:145], v[166:167], 0, s[46:47]
	s_addc_u32 s3, s21, 0
	s_add_i32 s20, s44, s24
	global_load_lds_dwordx4 v[144:145], off
	v_lshl_add_u64 v[144:145], s[2:3], 0, v[0:1]
	s_mov_b32 m0, s20
	s_nop 0
	global_load_lds_dwordx4 v[144:145], off
	v_lshl_add_u64 v[144:145], s[2:3], 0, v[138:139]
	s_add_i32 m0, s20, 0x2000
	s_nop 0
	global_load_lds_dwordx4 v[144:145], off
	v_lshl_add_u64 v[144:145], v[196:197], 0, s[46:47]
	s_mov_b32 m0, s31
	s_nop 0
	global_load_lds_dwordx4 v[144:145], off
	v_lshl_add_u64 v[144:145], v[242:243], 0, s[46:47]
	s_mov_b32 m0, s34
	s_nop 0
	global_load_lds_dwordx4 v[144:145], off
	s_waitcnt vmcnt(8)
	s_waitcnt lgkmcnt(0)
	s_barrier
	s_waitcnt lgkmcnt(0)
	v_mfma_f32_16x16x32_bf16 v[62:65], v[150:153], v[210:213], v[62:65]
	v_mfma_f32_16x16x32_bf16 v[58:61], v[158:161], v[210:213], v[58:61]
	v_mfma_f32_16x16x32_bf16 v[46:49], v[150:153], v[218:221], v[46:49]
	v_mfma_f32_16x16x32_bf16 v[42:45], v[158:161], v[218:221], v[42:45]
	v_mfma_f32_16x16x32_bf16 v[30:33], v[150:153], v[226:229], v[30:33]
	v_mfma_f32_16x16x32_bf16 v[26:29], v[158:161], v[226:229], v[26:29]
	v_mfma_f32_16x16x32_bf16 v[14:17], v[150:153], v[234:237], v[14:17]
	v_mfma_f32_16x16x32_bf16 v[10:13], v[158:161], v[234:237], v[10:13]
	v_mfma_f32_16x16x32_bf16 v[62:65], v[154:157], v[214:217], v[62:65]
	v_mfma_f32_16x16x32_bf16 v[58:61], v[162:165], v[214:217], v[58:61]
	v_mfma_f32_16x16x32_bf16 v[46:49], v[154:157], v[222:225], v[46:49]
	v_mfma_f32_16x16x32_bf16 v[42:45], v[162:165], v[222:225], v[42:45]
	v_mfma_f32_16x16x32_bf16 v[30:33], v[154:157], v[230:233], v[30:33]
	v_mfma_f32_16x16x32_bf16 v[26:29], v[162:165], v[230:233], v[26:29]
	v_mfma_f32_16x16x32_bf16 v[14:17], v[154:157], v[238:241], v[14:17]
	v_mfma_f32_16x16x32_bf16 v[10:13], v[162:165], v[238:241], v[10:13]
	v_mfma_f32_16x16x32_bf16 v[54:57], v[188:191], v[210:213], v[54:57]
	v_mfma_f32_16x16x32_bf16 v[50:53], v[202:205], v[210:213], v[50:53]
	v_mfma_f32_16x16x32_bf16 v[38:41], v[188:191], v[218:221], v[38:41]
	v_mfma_f32_16x16x32_bf16 v[34:37], v[202:205], v[218:221], v[34:37]
	v_mfma_f32_16x16x32_bf16 v[22:25], v[188:191], v[226:229], v[22:25]
	v_mfma_f32_16x16x32_bf16 v[18:21], v[202:205], v[226:229], v[18:21]
	v_mfma_f32_16x16x32_bf16 v[6:9], v[188:191], v[234:237], v[6:9]
	v_mfma_f32_16x16x32_bf16 v[2:5], v[202:205], v[234:237], v[2:5]
	v_mfma_f32_16x16x32_bf16 v[54:57], v[192:195], v[214:217], v[54:57]
	v_mfma_f32_16x16x32_bf16 v[50:53], v[206:209], v[214:217], v[50:53]
	v_mfma_f32_16x16x32_bf16 v[38:41], v[192:195], v[222:225], v[38:41]
	v_mfma_f32_16x16x32_bf16 v[34:37], v[206:209], v[222:225], v[34:37]
	v_mfma_f32_16x16x32_bf16 v[22:25], v[192:195], v[230:233], v[22:25]
	v_mfma_f32_16x16x32_bf16 v[18:21], v[206:209], v[230:233], v[18:21]
	v_mfma_f32_16x16x32_bf16 v[6:9], v[192:195], v[238:241], v[6:9]
	v_mfma_f32_16x16x32_bf16 v[2:5], v[206:209], v[238:241], v[2:5]
	s_barrier
	s_add_i32 s42, s42, 2
	s_add_u32 s18, s18, 0x100
	s_addc_u32 s19, s19, 0
	s_add_u32 s40, s40, 0x100
	s_addc_u32 s41, s41, 0
	s_cmp_gt_u32 s42, 13
	s_cbranch_scc0 .LBB0_1025
	s_and_b64 vcc, exec, s[8:9]
	s_cbranch_vccz .LBB0_1028
	s_barrier

; #define PG8_STAGE(bufoff, gbase, voff) do { _Pragma("unroll") for (int _i = 0; _i < 2; ++_i) \
;         __builtin_amdgcn_global_load_lds((const unsigned*)((const char*)(gbase) + (voff)[_i]), (PG8_LAS unsigned*)(lds + (bufoff) + ldsw + _i * 8192), 16, 0, 0); } while (0)
; #define PG8_LDA(dst, b, h) do { _Pragma("unroll") for (int m = 0; m < 4; ++m) _Pragma("unroll") for (int k = 0; k < 2; ++k) dst[m][k] = *(const PG8_LAS bf16x8*)(lds + PG8_SA(b, h) + aoff + m * 2048 + k * 1024); } while (0)
; #define PG8_LDB(dst, b, h) do { _Pragma("unroll") for (int n = 0; n < 2; ++n) _Pragma("unroll") for (int k = 0; k < 2; ++k) dst[n][k] = *(const PG8_LAS bf16x8*)(lds + PG8_SB(b, h) + boff + n * 2048 + k * 1024); } while (0)
; #define PG8_MMA(ai, bj, At, Bt) do { __builtin_amdgcn_s_setprio(1); _Pragma("unroll") for (int m = 0; m < 4; ++m) _Pragma("unroll") for (int n = 0; n < 2; ++n) _Pragma("unroll") for (int k = 0; k < 2; ++k) \
;         acc[ai][bj][m][n] = __builtin_amdgcn_mfma_f32_16x16x32_bf16(Bt[n][k], At[m][k], acc[ai][bj][m][n], 0, 0, 0); __builtin_amdgcn_s_setprio(0); } while (0)
; #define PG8_WAIT_V(n) asm volatile("s_waitcnt vmcnt(" #n ")" ::: "memory")
; #define PG8_WAIT_L(n) asm volatile("s_waitcnt lgkmcnt(" #n ")" ::: "memory")
; #define PG8_BAR __builtin_amdgcn_s_barrier()
; #define PG8_SCHED __builtin_amdgcn_sched_barrier(0)
; template <class Epi, class Sched, bool ALIGN_EPI = false, bool SP2 = false>
; __device__ __forceinline__ void gemm_phase(PG8_LAS unsigned char* lds, const Gemm g, const Sched& S, const Epi& E) {
;     ...
;         for (int t = 0; t < nt; t += 2) {
;             const bool last = (t == nt - 2);
;             const char* a1 = cA + (size_t)(t + 1) * kstep;
;             const char* a2 = last ? nA : cA + (size_t)(t + 2) * kstep; const char* b2 = last ? nB : cB + (size_t)(t + 2) * kstep;
;             const char* a3 = a2 + kstep; const char* b3 = b2 + kstep;
;             if (last && has_next) S.a_ready(nxt);
;             if constexpr (SP2) {
;             PG8_LDB(B0, 0, 0); PG8_LDB(B1, 0, 1); PG8_SCHED; PG8_LDA(At, 0, 0); PG8_STAGE(PG8_SA(1, 1), a1 + hstep, voffA);
;             PG8_WAIT_V(8); PG8_WAIT_L(0); PG8_BAR; PG8_MMA(0, 0, At, B0); PG8_MMA(0, 1, At, B1); PG8_BAR; PG8_SCHED;
;             PG8_LDA(At, 0, 1); PG8_STAGE(PG8_SB(0, 0), b2, voffB); PG8_STAGE(PG8_SB(0, 1), b2 + hstep, voffB); PG8_STAGE(PG8_SA(0, 0), a2, voffA);
.LBB0_1047:
	s_add_u32 s2, s20, 0xfffc0080
	s_addc_u32 s3, s21, -1
	s_add_i32 s46, 0, 0x10000
	s_cmp_eq_u32 s45, 12
	s_cselect_b32 s25, s15, s3
	s_cselect_b32 s24, s41, s2
	v_add_u32_e32 v148, s46, v151
	s_cselect_b32 s23, s13, s44
	s_cselect_b32 s22, s42, s43
	s_add_i32 s47, 0, 0x14000
	ds_read_b128 v[144:147], v148
	ds_read_b128 v[154:157], v148 offset:1024
	ds_read_b128 v[158:161], v148 offset:2048
	ds_read_b128 v[162:165], v148 offset:3072
	v_add_u32_e32 v148, s47, v151
	ds_read_b128 v[188:191], v148
	ds_read_b128 v[192:195], v148 offset:1024
	ds_read_b128 v[202:205], v148 offset:2048
	ds_read_b128 v[206:209], v148 offset:3072
	v_lshl_add_u64 v[148:149], s[20:21], 0, v[140:141]
	s_add_i32 m0, s29, 0xc000
	ds_read_b128 v[210:213], v153
	ds_read_b128 v[214:217], v153 offset:1024
	ds_read_b128 v[218:221], v153 offset:2048
	ds_read_b128 v[222:225], v153 offset:3072
	ds_read_b128 v[226:229], v153 offset:4096
	ds_read_b128 v[230:233], v153 offset:5120
	ds_read_b128 v[234:237], v153 offset:6144
	ds_read_b128 v[238:241], v153 offset:7168
	global_load_lds_dwordx4 v[148:149], off
	v_lshl_add_u64 v[148:149], s[20:21], 0, v[142:143]
	s_add_i32 m0, s29, 0xe000
	s_nop 0
	global_load_lds_dwordx4 v[148:149], off
	s_waitcnt vmcnt(8)
	s_waitcnt lgkmcnt(0)
	s_barrier
	s_waitcnt lgkmcnt(0)
	v_mfma_f32_16x16x32_bf16 v[126:129], v[144:147], v[210:213], v[126:129]
	v_mfma_f32_16x16x32_bf16 v[122:125], v[158:161], v[210:213], v[122:125]
	v_mfma_f32_16x16x32_bf16 v[110:113], v[144:147], v[218:221], v[110:113]
	v_mfma_f32_16x16x32_bf16 v[106:109], v[158:161], v[218:221], v[106:109]
	v_mfma_f32_16x16x32_bf16 v[94:97], v[144:147], v[226:229], v[94:97]
	v_mfma_f32_16x16x32_bf16 v[90:93], v[158:161], v[226:229], v[90:93]
	v_mfma_f32_16x16x32_bf16 v[78:81], v[144:147], v[234:237], v[78:81]
	v_mfma_f32_16x16x32_bf16 v[74:77], v[158:161], v[234:237], v[74:77]
	v_mfma_f32_16x16x32_bf16 v[126:129], v[154:157], v[214:217], v[126:129]
	v_mfma_f32_16x16x32_bf16 v[122:125], v[162:165], v[214:217], v[122:125]
	v_mfma_f32_16x16x32_bf16 v[110:113], v[154:157], v[222:225], v[110:113]
	v_mfma_f32_16x16x32_bf16 v[106:109], v[162:165], v[222:225], v[106:109]
	v_mfma_f32_16x16x32_bf16 v[94:97], v[154:157], v[230:233], v[94:97]
	v_mfma_f32_16x16x32_bf16 v[90:93], v[162:165], v[230:233], v[90:93]
	v_mfma_f32_16x16x32_bf16 v[78:81], v[154:157], v[238:241], v[78:81]
	v_mfma_f32_16x16x32_bf16 v[74:77], v[162:165], v[238:241], v[74:77]
	v_mfma_f32_16x16x32_bf16 v[118:121], v[188:191], v[210:213], v[118:121]
	v_mfma_f32_16x16x32_bf16 v[114:117], v[202:205], v[210:213], v[114:117]
	v_mfma_f32_16x16x32_bf16 v[102:105], v[188:191], v[218:221], v[102:105]
	v_mfma_f32_16x16x32_bf16 v[98:101], v[202:205], v[218:221], v[98:101]
	v_mfma_f32_16x16x32_bf16 v[86:89], v[188:191], v[226:229], v[86:89]
	v_mfma_f32_16x16x32_bf16 v[82:85], v[202:205], v[226:229], v[82:85]
	v_mfma_f32_16x16x32_bf16 v[70:73], v[188:191], v[234:237], v[70:73]
	v_mfma_f32_16x16x32_bf16 v[66:69], v[202:205], v[234:237], v[66:69]
	v_mfma_f32_16x16x32_bf16 v[118:121], v[192:195], v[214:217], v[118:121]
	v_mfma_f32_16x16x32_bf16 v[114:117], v[206:209], v[214:217], v[114:117]
	v_mfma_f32_16x16x32_bf16 v[102:105], v[192:195], v[222:225], v[102:105]
	v_mfma_f32_16x16x32_bf16 v[98:101], v[206:209], v[222:225], v[98:101]
	v_mfma_f32_16x16x32_bf16 v[86:89], v[192:195], v[230:233], v[86:89]
	v_mfma_f32_16x16x32_bf16 v[82:85], v[206:209], v[230:233], v[82:85]
	v_mfma_f32_16x16x32_bf16 v[70:73], v[192:195], v[238:241], v[70:73]
	v_mfma_f32_16x16x32_bf16 v[66:69], v[206:209], v[238:241], v[66:69]
	s_barrier
	s_add_i32 s2, s46, s28
	v_lshl_add_u64 v[148:149], s[22:23], 0, v[0:1]
	s_mov_b32 m0, s2
	ds_read_b128 v[210:213], v153 offset:16384
	ds_read_b128 v[214:217], v153 offset:17408
	ds_read_b128 v[218:221], v153 offset:18432
	ds_read_b128 v[222:225], v153 offset:19456
	ds_read_b128 v[226:229], v153 offset:20480
	ds_read_b128 v[230:233], v153 offset:21504
	ds_read_b128 v[234:237], v153 offset:22528
	ds_read_b128 v[238:241], v153 offset:23552
	global_load_lds_dwordx4 v[148:149], off
	s_add_i32 m0, s2, 0x2000
	s_add_u32 s2, s22, 0x40000
	v_lshl_add_u64 v[166:167], s[22:23], 0, v[138:139]
	s_addc_u32 s3, s23, 0
	s_add_i32 s46, s47, s28
	global_load_lds_dwordx4 v[166:167], off
	v_lshl_add_u64 v[196:197], s[2:3], 0, v[0:1]
	s_mov_b32 m0, s46
	v_lshl_add_u64 v[242:243], s[24:25], 0, v[138:139]
	global_load_lds_dwordx4 v[196:197], off
	v_lshl_add_u64 v[196:197], s[2:3], 0, v[138:139]
	s_add_i32 m0, s46, 0x2000
	s_nop 0
	global_load_lds_dwordx4 v[196:197], off
	v_lshl_add_u64 v[196:197], s[24:25], 0, v[0:1]
	s_mov_b32 m0, s29
	s_nop 0
	global_load_lds_dwordx4 v[196:197], off
	s_mov_b32 m0, s30
	s_nop 0
	global_load_lds_dwordx4 v[242:243], off
	s_waitcnt vmcnt(8)
	s_waitcnt lgkmcnt(0)
	s_barrier
; #define PG8_STAGE(bufoff, gbase, voff) do { _Pragma("unroll") for (int _i = 0; _i < 2; ++_i) \
;         __builtin_amdgcn_global_load_lds((const unsigned*)((const char*)(gbase) + (voff)[_i]), (PG8_LAS unsigned*)(lds + (bufoff) + ldsw + _i * 8192), 16, 0, 0); } while (0)
; #define PG8_LDA(dst, b, h) do { _Pragma("unroll") for (int m = 0; m < 4; ++m) _Pragma("unroll") for (int k = 0; k < 2; ++k) dst[m][k] = *(const PG8_LAS bf16x8*)(lds + PG8_SA(b, h) + aoff + m * 2048 + k * 1024); } while (0)
; #define PG8_LDB(dst, b, h) do { _Pragma("unroll") for (int n = 0; n < 2; ++n) _Pragma("unroll") for (int k = 0; k < 2; ++k) dst[n][k] = *(const PG8_LAS bf16x8*)(lds + PG8_SB(b, h) + boff + n * 2048 + k * 1024); } while (0)
; #define PG8_MMA(ai, bj, At, Bt) do { __builtin_amdgcn_s_setprio(1); _Pragma("unroll") for (int m = 0; m < 4; ++m) _Pragma("unroll") for (int n = 0; n < 2; ++n) _Pragma("unroll") for (int k = 0; k < 2; ++k) \
;         acc[ai][bj][m][n] = __builtin_amdgcn_mfma_f32_16x16x32_bf16(Bt[n][k], At[m][k], acc[ai][bj][m][n], 0, 0, 0); __builtin_amdgcn_s_setprio(0); } while (0)
; #define PG8_WAIT_V(n) asm volatile("s_waitcnt vmcnt(" #n ")" ::: "memory")
; #define PG8_WAIT_L(n) asm volatile("s_waitcnt lgkmcnt(" #n ")" ::: "memory")
; #define PG8_BAR __builtin_amdgcn_s_barrier()
; #define PG8_SCHED __builtin_amdgcn_sched_barrier(0)
; template <class Epi, class Sched, bool ALIGN_EPI = false, bool SP2 = false>
; __device__ __forceinline__ void gemm_phase(PG8_LAS unsigned char* lds, const Gemm g, const Sched& S, const Epi& E) {
;     ...
;             PG8_WAIT_V(8); PG8_WAIT_L(0); PG8_BAR; PG8_MMA(1, 0, At, B0); PG8_MMA(1, 1, At, B1); PG8_BAR; PG8_SCHED;
;             PG8_LDB(B0, 1, 0); PG8_LDB(B1, 1, 1); PG8_SCHED; PG8_LDA(At, 1, 0); PG8_STAGE(PG8_SA(0, 1), a2 + hstep, voffA);
;             PG8_WAIT_V(8); PG8_WAIT_L(0); PG8_BAR; PG8_MMA(0, 0, At, B0); PG8_MMA(0, 1, At, B1); PG8_BAR; PG8_SCHED;
	s_waitcnt lgkmcnt(0)
	v_mfma_f32_16x16x32_bf16 v[62:65], v[144:147], v[210:213], v[62:65]
	v_mfma_f32_16x16x32_bf16 v[58:61], v[158:161], v[210:213], v[58:61]
	v_mfma_f32_16x16x32_bf16 v[46:49], v[144:147], v[218:221], v[46:49]
	v_mfma_f32_16x16x32_bf16 v[42:45], v[158:161], v[218:221], v[42:45]
	v_mfma_f32_16x16x32_bf16 v[30:33], v[144:147], v[226:229], v[30:33]
	v_mfma_f32_16x16x32_bf16 v[26:29], v[158:161], v[226:229], v[26:29]
	v_mfma_f32_16x16x32_bf16 v[14:17], v[144:147], v[234:237], v[14:17]
	v_mfma_f32_16x16x32_bf16 v[10:13], v[158:161], v[234:237], v[10:13]
	v_mfma_f32_16x16x32_bf16 v[62:65], v[154:157], v[214:217], v[62:65]
	v_mfma_f32_16x16x32_bf16 v[58:61], v[162:165], v[214:217], v[58:61]
	v_mfma_f32_16x16x32_bf16 v[46:49], v[154:157], v[222:225], v[46:49]
	v_mfma_f32_16x16x32_bf16 v[42:45], v[162:165], v[222:225], v[42:45]
	v_mfma_f32_16x16x32_bf16 v[30:33], v[154:157], v[230:233], v[30:33]
	v_mfma_f32_16x16x32_bf16 v[26:29], v[162:165], v[230:233], v[26:29]
	v_mfma_f32_16x16x32_bf16 v[14:17], v[154:157], v[238:241], v[14:17]
	v_mfma_f32_16x16x32_bf16 v[10:13], v[162:165], v[238:241], v[10:13]
	v_mfma_f32_16x16x32_bf16 v[54:57], v[188:191], v[210:213], v[54:57]
	v_mfma_f32_16x16x32_bf16 v[50:53], v[202:205], v[210:213], v[50:53]
	v_mfma_f32_16x16x32_bf16 v[38:41], v[188:191], v[218:221], v[38:41]
	v_mfma_f32_16x16x32_bf16 v[34:37], v[202:205], v[218:221], v[34:37]
	v_mfma_f32_16x16x32_bf16 v[22:25], v[188:191], v[226:229], v[22:25]
	v_mfma_f32_16x16x32_bf16 v[18:21], v[202:205], v[226:229], v[18:21]
	v_mfma_f32_16x16x32_bf16 v[6:9], v[188:191], v[234:237], v[6:9]
	v_mfma_f32_16x16x32_bf16 v[2:5], v[202:205], v[234:237], v[2:5]
	v_mfma_f32_16x16x32_bf16 v[54:57], v[192:195], v[214:217], v[54:57]
	v_mfma_f32_16x16x32_bf16 v[50:53], v[206:209], v[214:217], v[50:53]
	v_mfma_f32_16x16x32_bf16 v[38:41], v[192:195], v[222:225], v[38:41]
	v_mfma_f32_16x16x32_bf16 v[34:37], v[206:209], v[222:225], v[34:37]
	v_mfma_f32_16x16x32_bf16 v[22:25], v[192:195], v[230:233], v[22:25]
	v_mfma_f32_16x16x32_bf16 v[18:21], v[206:209], v[230:233], v[18:21]
	v_mfma_f32_16x16x32_bf16 v[6:9], v[192:195], v[238:241], v[6:9]
	v_mfma_f32_16x16x32_bf16 v[2:5], v[206:209], v[238:241], v[2:5]
	s_barrier
	s_add_i32 s46, 0, 0x18000
	s_add_i32 s47, 0, 0x1c000
	v_add_u32_e32 v162, s46, v151
	v_add_u32_e32 v206, s47, v151
	ds_read_b128 v[144:147], v162
	ds_read_b128 v[154:157], v162 offset:1024
	ds_read_b128 v[158:161], v162 offset:2048
	ds_read_b128 v[162:165], v162 offset:3072
	ds_read_b128 v[188:191], v206
	ds_read_b128 v[192:195], v206 offset:1024
	ds_read_b128 v[202:205], v206 offset:2048
	ds_read_b128 v[206:209], v206 offset:3072
	s_add_u32 s2, s24, 0x40000
	s_addc_u32 s3, s25, 0
	s_mov_b32 m0, s31
	v_lshl_add_u64 v[244:245], s[2:3], 0, v[0:1]
	ds_read_b128 v[210:213], v153 offset:32768
	ds_read_b128 v[214:217], v153 offset:33792
	ds_read_b128 v[218:221], v153 offset:34816
	ds_read_b128 v[222:225], v153 offset:35840
	ds_read_b128 v[226:229], v153 offset:36864
	ds_read_b128 v[230:233], v153 offset:37888
	ds_read_b128 v[234:237], v153 offset:38912
	ds_read_b128 v[238:241], v153 offset:39936
	global_load_lds_dwordx4 v[244:245], off
	v_lshl_add_u64 v[244:245], s[2:3], 0, v[138:139]
	s_mov_b32 m0, s34
	s_nop 0
	global_load_lds_dwordx4 v[244:245], off
	s_waitcnt vmcnt(8)
	s_waitcnt lgkmcnt(0)
	s_barrier
	s_waitcnt lgkmcnt(0)
	v_mfma_f32_16x16x32_bf16 v[126:129], v[144:147], v[210:213], v[126:129]
	v_mfma_f32_16x16x32_bf16 v[122:125], v[158:161], v[210:213], v[122:125]
	v_mfma_f32_16x16x32_bf16 v[110:113], v[144:147], v[218:221], v[110:113]
	v_mfma_f32_16x16x32_bf16 v[106:109], v[158:161], v[218:221], v[106:109]
	v_mfma_f32_16x16x32_bf16 v[94:97], v[144:147], v[226:229], v[94:97]
	v_mfma_f32_16x16x32_bf16 v[90:93], v[158:161], v[226:229], v[90:93]
	v_mfma_f32_16x16x32_bf16 v[78:81], v[144:147], v[234:237], v[78:81]
	v_mfma_f32_16x16x32_bf16 v[74:77], v[158:161], v[234:237], v[74:77]
	v_mfma_f32_16x16x32_bf16 v[126:129], v[154:157], v[214:217], v[126:129]
	v_mfma_f32_16x16x32_bf16 v[122:125], v[162:165], v[214:217], v[122:125]
	v_mfma_f32_16x16x32_bf16 v[110:113], v[154:157], v[222:225], v[110:113]
	v_mfma_f32_16x16x32_bf16 v[106:109], v[162:165], v[222:225], v[106:109]
	v_mfma_f32_16x16x32_bf16 v[94:97], v[154:157], v[230:233], v[94:97]
	v_mfma_f32_16x16x32_bf16 v[90:93], v[162:165], v[230:233], v[90:93]
	v_mfma_f32_16x16x32_bf16 v[78:81], v[154:157], v[238:241], v[78:81]
	v_mfma_f32_16x16x32_bf16 v[74:77], v[162:165], v[238:241], v[74:77]
	v_mfma_f32_16x16x32_bf16 v[118:121], v[188:191], v[210:213], v[118:121]
	v_mfma_f32_16x16x32_bf16 v[114:117], v[202:205], v[210:213], v[114:117]
	v_mfma_f32_16x16x32_bf16 v[102:105], v[188:191], v[218:221], v[102:105]
	v_mfma_f32_16x16x32_bf16 v[98:101], v[202:205], v[218:221], v[98:101]
	v_mfma_f32_16x16x32_bf16 v[86:89], v[188:191], v[226:229], v[86:89]
	v_mfma_f32_16x16x32_bf16 v[82:85], v[202:205], v[226:229], v[82:85]
	v_mfma_f32_16x16x32_bf16 v[70:73], v[188:191], v[234:237], v[70:73]
	v_mfma_f32_16x16x32_bf16 v[66:69], v[202:205], v[234:237], v[66:69]
	v_mfma_f32_16x16x32_bf16 v[118:121], v[192:195], v[214:217], v[118:121]
	v_mfma_f32_16x16x32_bf16 v[114:117], v[206:209], v[214:217], v[114:117]
	v_mfma_f32_16x16x32_bf16 v[102:105], v[192:195], v[222:225], v[102:105]
	v_mfma_f32_16x16x32_bf16 v[98:101], v[206:209], v[222:225], v[98:101]
	v_mfma_f32_16x16x32_bf16 v[86:89], v[192:195], v[230:233], v[86:89]
	v_mfma_f32_16x16x32_bf16 v[82:85], v[206:209], v[230:233], v[82:85]
	v_mfma_f32_16x16x32_bf16 v[70:73], v[192:195], v[238:241], v[70:73]
	v_mfma_f32_16x16x32_bf16 v[66:69], v[206:209], v[238:241], v[66:69]
	s_barrier
; #define PG8_STAGE(bufoff, gbase, voff) do { _Pragma("unroll") for (int _i = 0; _i < 2; ++_i) \
;         __builtin_amdgcn_global_load_lds((const unsigned*)((const char*)(gbase) + (voff)[_i]), (PG8_LAS unsigned*)(lds + (bufoff) + ldsw + _i * 8192), 16, 0, 0); } while (0)
; #define PG8_LDA(dst, b, h) do { _Pragma("unroll") for (int m = 0; m < 4; ++m) _Pragma("unroll") for (int k = 0; k < 2; ++k) dst[m][k] = *(const PG8_LAS bf16x8*)(lds + PG8_SA(b, h) + aoff + m * 2048 + k * 1024); } while (0)
; #define PG8_MMA(ai, bj, At, Bt) do { __builtin_amdgcn_s_setprio(1); _Pragma("unroll") for (int m = 0; m < 4; ++m) _Pragma("unroll") for (int n = 0; n < 2; ++n) _Pragma("unroll") for (int k = 0; k < 2; ++k) \
;         acc[ai][bj][m][n] = __builtin_amdgcn_mfma_f32_16x16x32_bf16(Bt[n][k], At[m][k], acc[ai][bj][m][n], 0, 0, 0); __builtin_amdgcn_s_setprio(0); } while (0)
; #define PG8_WAIT_V(n) asm volatile("s_waitcnt vmcnt(" #n ")" ::: "memory")
; #define PG8_WAIT_L(n) asm volatile("s_waitcnt lgkmcnt(" #n ")" ::: "memory")
; #define PG8_BAR __builtin_amdgcn_s_barrier()
; #define PG8_SCHED __builtin_amdgcn_sched_barrier(0)
; template <class Epi, class Sched, bool ALIGN_EPI = false, bool SP2 = false>
; __device__ __forceinline__ void gemm_phase(PG8_LAS unsigned char* lds, const Gemm g, const Sched& S, const Epi& E) {
;     ...
;             PG8_LDA(At, 1, 1); PG8_STAGE(PG8_SB(1, 0), b3, voffB); PG8_STAGE(PG8_SB(1, 1), b3 + hstep, voffB); PG8_STAGE(PG8_SA(1, 0), a3, voffA);
;             PG8_WAIT_V(8); PG8_WAIT_L(0); PG8_BAR; PG8_MMA(1, 0, At, B0); PG8_MMA(1, 1, At, B1); PG8_BAR; PG8_SCHED;
	s_add_i32 s2, s46, s28
	v_lshl_add_u64 v[148:149], v[148:149], 0, s[48:49]
	s_mov_b32 m0, s2
	ds_read_b128 v[210:213], v153 offset:49152
	ds_read_b128 v[214:217], v153 offset:50176
	ds_read_b128 v[218:221], v153 offset:51200
	ds_read_b128 v[222:225], v153 offset:52224
	ds_read_b128 v[226:229], v153 offset:53248
	ds_read_b128 v[230:233], v153 offset:54272
	ds_read_b128 v[234:237], v153 offset:55296
	ds_read_b128 v[238:241], v153 offset:56320
	global_load_lds_dwordx4 v[148:149], off
	s_add_i32 m0, s2, 0x2000
	s_add_u32 s2, s22, 0x40080
	v_lshl_add_u64 v[148:149], v[166:167], 0, s[48:49]
	s_addc_u32 s3, s23, 0
	s_add_i32 s22, s47, s28
	global_load_lds_dwordx4 v[148:149], off
	v_lshl_add_u64 v[148:149], s[2:3], 0, v[0:1]
	s_mov_b32 m0, s22
	s_nop 0
	global_load_lds_dwordx4 v[148:149], off
	v_lshl_add_u64 v[148:149], s[2:3], 0, v[138:139]
	s_add_i32 m0, s22, 0x2000
	s_nop 0
	global_load_lds_dwordx4 v[148:149], off
	v_lshl_add_u64 v[148:149], v[196:197], 0, s[48:49]
	s_mov_b32 m0, s36
	s_nop 0
	global_load_lds_dwordx4 v[148:149], off
	v_lshl_add_u64 v[148:149], v[242:243], 0, s[48:49]
	s_mov_b32 m0, s37
	s_nop 0
	global_load_lds_dwordx4 v[148:149], off
	s_waitcnt vmcnt(8)
	s_waitcnt lgkmcnt(0)
	s_barrier
	s_waitcnt lgkmcnt(0)
	v_mfma_f32_16x16x32_bf16 v[62:65], v[144:147], v[210:213], v[62:65]
	v_mfma_f32_16x16x32_bf16 v[58:61], v[158:161], v[210:213], v[58:61]
	v_mfma_f32_16x16x32_bf16 v[46:49], v[144:147], v[218:221], v[46:49]
	v_mfma_f32_16x16x32_bf16 v[42:45], v[158:161], v[218:221], v[42:45]
	v_mfma_f32_16x16x32_bf16 v[30:33], v[144:147], v[226:229], v[30:33]
	v_mfma_f32_16x16x32_bf16 v[26:29], v[158:161], v[226:229], v[26:29]
	v_mfma_f32_16x16x32_bf16 v[14:17], v[144:147], v[234:237], v[14:17]
	v_mfma_f32_16x16x32_bf16 v[10:13], v[158:161], v[234:237], v[10:13]
	v_mfma_f32_16x16x32_bf16 v[62:65], v[154:157], v[214:217], v[62:65]
	v_mfma_f32_16x16x32_bf16 v[58:61], v[162:165], v[214:217], v[58:61]
	v_mfma_f32_16x16x32_bf16 v[46:49], v[154:157], v[222:225], v[46:49]
	v_mfma_f32_16x16x32_bf16 v[42:45], v[162:165], v[222:225], v[42:45]
	v_mfma_f32_16x16x32_bf16 v[30:33], v[154:157], v[230:233], v[30:33]
	v_mfma_f32_16x16x32_bf16 v[26:29], v[162:165], v[230:233], v[26:29]
	v_mfma_f32_16x16x32_bf16 v[14:17], v[154:157], v[238:241], v[14:17]
	v_mfma_f32_16x16x32_bf16 v[10:13], v[162:165], v[238:241], v[10:13]
	v_mfma_f32_16x16x32_bf16 v[54:57], v[188:191], v[210:213], v[54:57]
	v_mfma_f32_16x16x32_bf16 v[50:53], v[202:205], v[210:213], v[50:53]
	v_mfma_f32_16x16x32_bf16 v[38:41], v[188:191], v[218:221], v[38:41]
	v_mfma_f32_16x16x32_bf16 v[34:37], v[202:205], v[218:221], v[34:37]
	v_mfma_f32_16x16x32_bf16 v[22:25], v[188:191], v[226:229], v[22:25]
	v_mfma_f32_16x16x32_bf16 v[18:21], v[202:205], v[226:229], v[18:21]
	v_mfma_f32_16x16x32_bf16 v[6:9], v[188:191], v[234:237], v[6:9]
	v_mfma_f32_16x16x32_bf16 v[2:5], v[202:205], v[234:237], v[2:5]
	v_mfma_f32_16x16x32_bf16 v[54:57], v[192:195], v[214:217], v[54:57]
	v_mfma_f32_16x16x32_bf16 v[50:53], v[206:209], v[214:217], v[50:53]
	v_mfma_f32_16x16x32_bf16 v[38:41], v[192:195], v[222:225], v[38:41]
	v_mfma_f32_16x16x32_bf16 v[34:37], v[206:209], v[222:225], v[34:37]
	v_mfma_f32_16x16x32_bf16 v[22:25], v[192:195], v[230:233], v[22:25]
	v_mfma_f32_16x16x32_bf16 v[18:21], v[206:209], v[230:233], v[18:21]
	v_mfma_f32_16x16x32_bf16 v[6:9], v[192:195], v[238:241], v[6:9]
	v_mfma_f32_16x16x32_bf16 v[2:5], v[206:209], v[238:241], v[2:5]
	s_barrier
	s_add_i32 s45, s45, 2
	s_add_u32 s20, s20, 0x100
	s_addc_u32 s21, s21, 0
	s_add_u32 s43, s43, 0x100
	s_addc_u32 s44, s44, 0
	s_cmp_gt_u32 s45, 13
	s_cbranch_scc0 .LBB0_1047
	s_and_b64 vcc, exec, s[10:11]
	s_cbranch_vccz .LBB0_1050
	s_barrier
